# plus: retention k-projection epilogue writes the transposed zeta-scaled KZ tile through a 2 KiB wave-private LDS scratch as 16-byte stores (2 per row group) instead of 16 two-byte global stores; stati
# baseline (speedup 1.0000x reference)
; __device__ __forceinline__ unsigned cvt_pk_bf16(float lo, float hi) { unsigned r; asm volatile("v_cvt_pk_bf16_f32 %0, %1, %2" : "=v"(r) : "v"(lo), "v"(hi)); return r; }
;     __device__ __forceinline__ void operator()(const Acc& acc, const Unit& u, int wr, int wc, int fr, int fq) const {
;     ...
;         const float lg = l2g[u.pn];
; #pragma unroll
;         for (int ai = 0; ai < 2; ++ai)
; #pragma unroll
;             for (int m = 0; m < 4; ++m) {
;                 const int row_in = ai * HALF + wr * 64 + m * 16 + fr, s = u.pm * BM + row_in;
;                 const float rs = mode == 0 ? exp2f((float)(row_in + 1) * lg) : 0.0625f;
;                 const f32x4* cp = cs + ((size_t)s * 128 + wc * 32 + 8 * fq) / 2;
;                 f32x4 t[4];
; #pragma unroll
;                 for (int i = 0; i < 4; ++i) t[i] = cp[i];
;                 float o1[8], o2[8];
; #pragma unroll
;                 for (int n = 0; n < 2; ++n)
; #pragma unroll
;                     for (int j = 0; j < 4; ++j) { const int e = n * 4 + j; const float co = t[e >> 1][(e & 1) * 2], si = t[e >> 1][(e & 1) * 2 + 1];
;                         const float x1 = acc[ai][0][m][n][j], x2 = acc[ai][1][m][n][j];
;                         o1[e] = (x1 * co - x2 * si) * rs; o2[e] = (x2 * co + x1 * si) * rs; }
;                 bf16_t* rowp = O + u.coff + (size_t)row_in * ldc + wc * 32 + 8 * fq;
;                 u32x4 w; w.x = cvt_pk_bf16(o1[0], o1[1]); w.y = cvt_pk_bf16(o1[2], o1[3]); w.z = cvt_pk_bf16(o1[4], o1[5]); w.w = cvt_pk_bf16(o1[6], o1[7]);
;                 *(u32x4*)rowp = w;
;                 w.x = cvt_pk_bf16(o2[0], o2[1]); w.y = cvt_pk_bf16(o2[2], o2[3]); w.z = cvt_pk_bf16(o2[4], o2[5]); w.w = cvt_pk_bf16(o2[6], o2[7]);
;                 *(u32x4*)(rowp + HALF) = w;
.LBB0_555:
	s_ashr_i32 s21, s20, 31
	s_lshl_b64 s[8:9], s[20:21], 2
	v_readlane_b32 s10, v248, 2
	v_readlane_b32 s11, v248, 3
	s_add_u32 s8, s10, s8
	v_mov_b32_e32 v128, v166
	v_mov_b32_e32 v129, v167
	s_addc_u32 s9, s11, s9
	global_load_dword v170, v145, s[8:9]
	v_lshlrev_b32_e32 v162, 3, v129
	v_add_u32_e32 v142, s96, v128
	v_add_u32_e32 v128, s50, v162
	v_ashrrev_i32_e32 v129, 31, v128
	v_lshlrev_b64 v[160:161], 9, v[128:129]
	v_add_u32_e32 v129, 1, v142
	v_cvt_f32_i32_e32 v129, v129
	s_lshl_b32 s20, s2, 8
	v_add_u32_e32 v128, s20, v142
	v_ashrrev_i32_e32 v163, 31, v162
	v_lshl_add_u64 v[164:165], v[162:163], 0, s[50:51]
	s_mov_b32 s19, s61
	s_lshl_b64 s[86:87], s[18:19], 1
	s_add_u32 s36, s94, s86
	s_addc_u32 s37, s95, s87
	s_waitcnt vmcnt(0)
	v_mul_f32_e32 v130, v170, v129
	v_cmp_gt_f32_e32 vcc, s75, v130
	s_nop 1
	v_cndmask_b32_e32 v131, 0, v190, vcc
	v_fmac_f32_e32 v131, v170, v129
	v_exp_f32_e32 v129, v131
	v_cndmask_b32_e32 v130, 0, v189, vcc
	s_andn2_b64 vcc, exec, s[46:47]
	v_ldexp_f32 v143, v129, v130
	v_ashrrev_i32_e32 v129, 31, v128
	v_lshlrev_b64 v[128:129], 7, v[128:129]
	v_lshl_add_u64 v[128:129], v[128:129], 0, v[164:165]
	v_lshl_add_u64 v[172:173], v[128:129], 3, s[16:17]
	global_load_dwordx4 v[128:131], v[172:173], off offset:48
	global_load_dwordx4 v[174:177], v[172:173], off offset:32
	global_load_dwordx4 v[178:181], v[172:173], off offset:16
	global_load_dwordx4 v[192:195], v[172:173], off
	v_add_u32_e32 v228, 16, v142
	v_add_u32_e32 v228, s20, v228
	v_ashrrev_i32_e32 v229, 31, v228
	v_lshlrev_b64 v[228:229], 7, v[228:229]
	v_lshl_add_u64 v[228:229], v[228:229], 0, v[164:165]
	v_lshl_add_u64 v[228:229], v[228:229], 3, s[16:17]
	global_load_dwordx4 v[212:215], v[228:229], off offset:48
	global_load_dwordx4 v[216:219], v[228:229], off offset:32
	global_load_dwordx4 v[220:223], v[228:229], off offset:16
	global_load_dwordx4 v[224:227], v[228:229], off
	v_mov_b32_e32 v172, v124
	v_mov_b32_e32 v173, v120
	v_cndmask_b32_e64 v143, v191, v143, s[44:45]
	s_waitcnt vmcnt(4)
	v_pk_mul_f32 v[172:173], v[172:173], v[192:193]
	s_nop 0
	v_sub_f32_e32 v171, v172, v173
	v_mov_b32_e32 v172, v120
	v_mov_b32_e32 v173, v124
	v_pk_mul_f32 v[172:173], v[172:173], v[192:193]
	v_mov_b32_e32 v124, v121
	v_add_f32_e32 v120, v173, v172
	v_mul_f32_e32 v172, v120, v143
	v_mov_b32_e32 v120, v125
	v_pk_mul_f32 v[192:193], v[120:121], v[194:195]
	v_pk_mul_f32 v[124:125], v[124:125], v[194:195]
	v_sub_f32_e32 v120, v192, v193
	v_add_f32_e32 v121, v125, v124
	v_mov_b32_e32 v124, v126
	v_mov_b32_e32 v125, v122
	v_mov_b32_e32 v192, v122
	v_mov_b32_e32 v193, v126
	v_pk_mul_f32 v[124:125], v[124:125], v[178:179]
	v_pk_mul_f32 v[178:179], v[192:193], v[178:179]
	v_sub_f32_e32 v124, v124, v125
	v_add_f32_e32 v122, v179, v178
	v_mul_f32_e32 v125, v122, v143
	v_mov_b32_e32 v122, v127
	v_mov_b32_e32 v126, v123
	v_pk_mul_f32 v[178:179], v[122:123], v[180:181]
	v_pk_mul_f32 v[126:127], v[126:127], v[180:181]
	v_sub_f32_e32 v122, v178, v179
	v_add_f32_e32 v123, v127, v126
	v_mov_b32_e32 v126, v116
	v_mov_b32_e32 v127, v112
	v_mov_b32_e32 v178, v112
	v_mov_b32_e32 v179, v116
	v_pk_mul_f32 v[126:127], v[126:127], v[174:175]
	v_pk_mul_f32 v[174:175], v[178:179], v[174:175]
	v_sub_f32_e32 v126, v126, v127
	v_add_f32_e32 v112, v175, v174
	v_mul_f32_e32 v127, v143, v112
	v_mov_b32_e32 v112, v117
	v_mov_b32_e32 v116, v113
	v_pk_mul_f32 v[174:175], v[112:113], v[176:177]
	v_pk_mul_f32 v[116:117], v[116:117], v[176:177]
	v_sub_f32_e32 v112, v174, v175
	v_add_f32_e32 v113, v117, v116
	v_mov_b32_e32 v116, v118
	v_mov_b32_e32 v117, v114
	v_mov_b32_e32 v174, v114
	v_mov_b32_e32 v175, v118
	v_pk_mul_f32 v[116:117], v[116:117], v[128:129]
	v_pk_mul_f32 v[128:129], v[174:175], v[128:129]
	v_sub_f32_e32 v116, v116, v117
	v_add_f32_e32 v114, v129, v128
	v_mul_f32_e32 v117, v143, v114
	v_mov_b32_e32 v114, v119
	v_mov_b32_e32 v118, v115
	v_pk_mul_f32 v[128:129], v[114:115], v[130:131]
	v_pk_mul_f32 v[118:119], v[118:119], v[130:131]
	v_sub_f32_e32 v114, v128, v129
	v_add_f32_e32 v115, v119, v118
	v_mul_f32_e32 v171, v171, v143
	v_mul_f32_e32 v120, v120, v143
	v_mul_f32_e32 v121, v121, v143
	v_mul_f32_e32 v124, v124, v143
	v_mul_f32_e32 v122, v122, v143
	v_mul_f32_e32 v123, v123, v143
	v_mul_f32_e32 v126, v143, v126
	v_mul_f32_e32 v112, v143, v112
	v_mul_f32_e32 v113, v143, v113
	v_mul_f32_e32 v116, v143, v116
	v_mul_f32_e32 v114, v143, v114
	v_mul_f32_e32 v115, v143, v115
	v_ashrrev_i32_e32 v143, 31, v142
	v_lshlrev_b64 v[118:119], s38, v[142:143]
	v_lshl_add_u64 v[118:119], v[118:119], 1, s[36:37]
	v_lshl_add_u64 v[118:119], v[118:119], 0, s[60:61]
	v_lshl_add_u64 v[118:119], v[162:163], 1, v[118:119]
	v_cvt_pk_bf16_f32 v128, v171, v120
	v_cvt_pk_bf16_f32 v129, v124, v122
	v_cvt_pk_bf16_f32 v130, v126, v112
	v_cvt_pk_bf16_f32 v131, v116, v114
	global_store_dwordx4 v[118:119], v[128:131], off
	s_nop 1
	v_cvt_pk_bf16_f32 v128, v172, v121
	v_cvt_pk_bf16_f32 v129, v125, v123
	v_cvt_pk_bf16_f32 v130, v127, v113
	v_cvt_pk_bf16_f32 v131, v117, v115
	global_store_dwordx4 v[118:119], v[128:131], off offset:256
	v_cndmask_b32_e64 v118, 0, 1, s[46:47]
	v_cmp_ne_u32_e64 s[42:43], 1, v118
	s_cbranch_vccnz .LBB0_557
; __device__ __forceinline__ unsigned cvt_pk_bf16(float lo, float hi) { unsigned r; asm volatile("v_cvt_pk_bf16_f32 %0, %1, %2" : "=v"(r) : "v"(lo), "v"(hi)); return r; }
;     __device__ __forceinline__ void operator()(const Acc& acc, const Unit& u, int wr, int wc, int fr, int fq) const {
;     ...
;                 if (mode == 1) {
;                     const float z = exp2f((float)(255 - row_in) * lg);
;                     bf16_t* kz = KZ + u.coff + (size_t)(wc * 32 + 8 * fq) * 256 + row_in;
; #pragma unroll
;                     for (int e = 0; e < 8; e += 2) { const unsigned p1 = cvt_pk_bf16(o1[e] * z, o1[e + 1] * z), p2 = cvt_pk_bf16(o2[e] * z, o2[e + 1] * z);
;                         kz[(size_t)e * 256] = (bf16_t)(p1 & 0xffffu); kz[(size_t)(e + 1) * 256] = (bf16_t)(p1 >> 16);
;                         kz[(size_t)(e + HALF) * 256] = (bf16_t)(p2 & 0xffffu); kz[(size_t)(e + 1 + HALF) * 256] = (bf16_t)(p2 >> 16); }
;                 }
	v_and_b32_e32 v234, 63, v182
	v_lshrrev_b32_e32 v235, 6, v182
	v_lshlrev_b32_e32 v235, 11, v235
	v_add_u32_e32 v235, 0x21900, v235
	v_and_b32_e32 v236, 15, v234
	v_lshrrev_b32_e32 v237, 4, v234
	v_lshlrev_b32_e32 v237, 8, v237
	v_lshl_add_u32 v237, v236, 1, v237
	v_add_u32_e32 v230, v235, v237
	v_lshrrev_b32_e32 v237, 1, v234
	v_lshlrev_b32_e32 v237, 5, v237
	v_and_b32_e32 v238, 1, v234
	v_lshl_add_u32 v237, v238, 4, v237
	v_add_u32_e32 v231, v235, v237
	v_lshrrev_b32_e32 v237, 1, v236
	v_lshlrev_b32_e32 v237, 9, v237
	v_and_b32_e32 v238, 1, v236
	v_lshl_add_u32 v237, v238, 4, v237
	v_lshlrev_b32_e32 v238, 1, v236
	v_sub_u32_e32 v232, v237, v238
	v_mov_b32_e32 v233, 0
	v_sub_u32_e32 v118, 0xff, v142
	v_cvt_f32_i32_e32 v118, v118
	s_add_u32 s2, s76, s86
	s_addc_u32 s3, s64, s87
	v_mul_f32_e32 v119, v170, v118
	v_cmp_gt_f32_e32 vcc, s75, v119
	s_nop 1
	v_cndmask_b32_e32 v119, 0, v190, vcc
	v_fmac_f32_e32 v119, v170, v118
	v_exp_f32_e32 v128, v119
	v_cndmask_b32_e32 v129, 0, v189, vcc
	v_lshl_add_u64 v[118:119], s[2:3], 0, v[160:161]
	v_lshl_add_u64 v[118:119], v[142:143], 1, v[118:119]
	v_ldexp_f32 v128, v128, v129
	v_mul_f32_e32 v129, v128, v171
	v_mul_f32_e32 v120, v128, v120
	v_cvt_pk_bf16_f32 v120, v129, v120
	v_mul_f32_e32 v129, v128, v172
	v_mul_f32_e32 v121, v128, v121
	v_cvt_pk_bf16_f32 v129, v129, v121
	ds_write_b16 v230, v120 offset:0
	ds_write_b16_d16_hi v230, v120 offset:32
	v_add_co_u32_e32 v120, vcc, s33, v118
	v_mul_f32_e32 v122, v128, v122
	s_nop 0
	v_addc_co_u32_e32 v121, vcc, 0, v119, vcc
	ds_write_b16 v230, v129 offset:1024
	ds_write_b16_d16_hi v230, v129 offset:1056
	v_mul_f32_e32 v124, v128, v124
	v_cvt_pk_bf16_f32 v122, v124, v122
	v_mul_f32_e32 v123, v128, v123
	v_mul_f32_e32 v124, v128, v125
	v_cvt_pk_bf16_f32 v123, v124, v123
	ds_write_b16 v230, v122 offset:64
	ds_write_b16_d16_hi v230, v122 offset:96
	ds_write_b16 v230, v123 offset:1088
	ds_write_b16_d16_hi v230, v123 offset:1120
	v_mul_f32_e32 v122, v128, v126
	v_mul_f32_e32 v112, v128, v112
	v_mul_f32_e32 v113, v128, v113
	v_cvt_pk_bf16_f32 v112, v122, v112
	v_mul_f32_e32 v122, v128, v127
	v_cvt_pk_bf16_f32 v113, v122, v113
	ds_write_b16 v230, v112 offset:128
	ds_write_b16_d16_hi v230, v112 offset:160
	ds_write_b16 v230, v113 offset:1152
	ds_write_b16_d16_hi v230, v113 offset:1184
	v_mul_f32_e32 v112, v128, v116
	v_mul_f32_e32 v113, v128, v114
	v_cvt_pk_bf16_f32 v112, v112, v113
	v_mul_f32_e32 v113, v128, v117
	v_mul_f32_e32 v114, v128, v115
	v_cvt_pk_bf16_f32 v113, v113, v114
	ds_write_b16 v230, v112 offset:192
	ds_write_b16_d16_hi v230, v112 offset:224
	ds_write_b16 v230, v113 offset:1216
	ds_write_b16_d16_hi v230, v113 offset:1248
	s_waitcnt lgkmcnt(0)
	ds_read_b128 v[234:237], v231
	ds_read_b128 v[238:241], v231 offset:1024
	v_lshl_add_u64 v[242:243], v[118:119], 0, v[232:233]
	s_waitcnt lgkmcnt(1)
	global_store_dwordx4 v[242:243], v[234:237], off
	v_lshl_add_u64 v[242:243], v[120:121], 0, v[232:233]
	s_waitcnt lgkmcnt(0)
	global_store_dwordx4 v[242:243], v[238:241], off
	s_waitcnt vmcnt(4)
	s_branch .Lrq_copy_1

; __device__ __forceinline__ unsigned cvt_pk_bf16(float lo, float hi) { unsigned r; asm volatile("v_cvt_pk_bf16_f32 %0, %1, %2" : "=v"(r) : "v"(lo), "v"(hi)); return r; }
;     __device__ __forceinline__ void operator()(const Acc& acc, const Unit& u, int wr, int wc, int fr, int fq) const {
;     ...
;             for (int m = 0; m < 4; ++m) {
;                 const int row_in = ai * HALF + wr * 64 + m * 16 + fr, s = u.pm * BM + row_in;
;                 const float rs = mode == 0 ? exp2f((float)(row_in + 1) * lg) : 0.0625f;
;                 const f32x4* cp = cs + ((size_t)s * 128 + wc * 32 + 8 * fq) / 2;
;                 f32x4 t[4];
; #pragma unroll
;                 for (int i = 0; i < 4; ++i) t[i] = cp[i];
;                 float o1[8], o2[8];
; #pragma unroll
;                 for (int n = 0; n < 2; ++n)
; #pragma unroll
;                     for (int j = 0; j < 4; ++j) { const int e = n * 4 + j; const float co = t[e >> 1][(e & 1) * 2], si = t[e >> 1][(e & 1) * 2 + 1];
;                         const float x1 = acc[ai][0][m][n][j], x2 = acc[ai][1][m][n][j];
;                         o1[e] = (x1 * co - x2 * si) * rs; o2[e] = (x2 * co + x1 * si) * rs; }
;                 bf16_t* rowp = O + u.coff + (size_t)row_in * ldc + wc * 32 + 8 * fq;
;                 u32x4 w; w.x = cvt_pk_bf16(o1[0], o1[1]); w.y = cvt_pk_bf16(o1[2], o1[3]); w.z = cvt_pk_bf16(o1[4], o1[5]); w.w = cvt_pk_bf16(o1[6], o1[7]);
;                 *(u32x4*)rowp = w;
;                 w.x = cvt_pk_bf16(o2[0], o2[1]); w.y = cvt_pk_bf16(o2[2], o2[3]); w.z = cvt_pk_bf16(o2[4], o2[5]); w.w = cvt_pk_bf16(o2[6], o2[7]);
;                 *(u32x4*)(rowp + HALF) = w;
;                 if (mode == 1) {
;                     const float z = exp2f((float)(255 - row_in) * lg);
;                     bf16_t* kz = KZ + u.coff + (size_t)(wc * 32 + 8 * fq) * 256 + row_in;
; #pragma unroll
;                     for (int e = 0; e < 8; e += 2) { const unsigned p1 = cvt_pk_bf16(o1[e] * z, o1[e + 1] * z), p2 = cvt_pk_bf16(o2[e] * z, o2[e + 1] * z);
;                         kz[(size_t)e * 256] = (bf16_t)(p1 & 0xffffu); kz[(size_t)(e + 1) * 256] = (bf16_t)(p1 >> 16);
;                         kz[(size_t)(e + HALF) * 256] = (bf16_t)(p2 & 0xffffu); kz[(size_t)(e + 1 + HALF) * 256] = (bf16_t)(p2 >> 16); }
;                 }
.Lrq_copy_1:
	v_add_u32_e32 v113, 17, v142
	v_cvt_f32_i32_e32 v113, v113
	v_add_u32_e32 v116, 16, v142
	v_add_u32_e32 v112, s20, v116
	v_mov_b32_e32 v172, v104
	v_mul_f32_e32 v114, v170, v113
	v_cmp_gt_f32_e32 vcc, s75, v114
	v_mov_b32_e32 v173, v108
	s_nop 0
	v_cndmask_b32_e32 v114, 0, v190, vcc
	v_fmac_f32_e32 v114, v170, v113
	v_exp_f32_e32 v113, v114
	v_cndmask_b32_e32 v114, 0, v189, vcc
	s_and_b64 vcc, exec, s[42:43]
	v_ldexp_f32 v117, v113, v114
	v_ashrrev_i32_e32 v113, 31, v112
	v_lshlrev_b64 v[112:113], 7, v[112:113]
	v_lshl_add_u64 v[112:113], v[112:113], 0, v[164:165]
	v_lshl_add_u64 v[118:119], v[112:113], 3, s[16:17]
	v_mov_b32_e32 v112, v212
	v_mov_b32_e32 v113, v213
	v_mov_b32_e32 v114, v214
	v_mov_b32_e32 v115, v215
	v_mov_b32_e32 v120, v216
	v_mov_b32_e32 v121, v217
	v_mov_b32_e32 v122, v218
	v_mov_b32_e32 v123, v219
	v_mov_b32_e32 v124, v220
	v_mov_b32_e32 v125, v221
	v_mov_b32_e32 v126, v222
	v_mov_b32_e32 v127, v223
	v_mov_b32_e32 v128, v224
	v_mov_b32_e32 v129, v225
	v_mov_b32_e32 v130, v226
	v_mov_b32_e32 v131, v227
	v_add_u32_e32 v228, 32, v142
	v_add_u32_e32 v228, s20, v228
	v_ashrrev_i32_e32 v229, 31, v228
	v_lshlrev_b64 v[228:229], 7, v[228:229]
	v_lshl_add_u64 v[228:229], v[228:229], 0, v[164:165]
	v_lshl_add_u64 v[228:229], v[228:229], 3, s[16:17]
	global_load_dwordx4 v[196:199], v[228:229], off offset:48
	global_load_dwordx4 v[200:203], v[228:229], off offset:32
	global_load_dwordx4 v[204:207], v[228:229], off offset:16
	global_load_dwordx4 v[208:211], v[228:229], off
	v_mov_b32_e32 v118, v108
	v_mov_b32_e32 v119, v104
	v_cndmask_b32_e64 v117, v191, v117, s[44:45]
	v_mov_b32_e32 v108, v105
	v_pk_mul_f32 v[118:119], v[118:119], v[128:129]
	v_pk_mul_f32 v[128:129], v[172:173], v[128:129]
	v_sub_f32_e32 v118, v118, v119
	v_add_f32_e32 v104, v129, v128
	v_mul_f32_e32 v119, v117, v104
	v_mov_b32_e32 v104, v109
	v_pk_mul_f32 v[128:129], v[104:105], v[130:131]
	v_pk_mul_f32 v[108:109], v[108:109], v[130:131]
	v_sub_f32_e32 v104, v128, v129
	v_add_f32_e32 v105, v109, v108
	v_mov_b32_e32 v108, v110
	v_mov_b32_e32 v109, v106
	v_mov_b32_e32 v128, v106
	v_mov_b32_e32 v129, v110
	v_pk_mul_f32 v[108:109], v[108:109], v[124:125]
	v_pk_mul_f32 v[124:125], v[128:129], v[124:125]
	v_sub_f32_e32 v108, v108, v109
	v_add_f32_e32 v106, v125, v124
	v_mul_f32_e32 v109, v117, v106
	v_mov_b32_e32 v106, v111
	v_mov_b32_e32 v110, v107
	v_pk_mul_f32 v[124:125], v[106:107], v[126:127]
	v_pk_mul_f32 v[110:111], v[110:111], v[126:127]
	v_sub_f32_e32 v106, v124, v125
	v_add_f32_e32 v107, v111, v110
	v_mov_b32_e32 v110, v96
	v_mov_b32_e32 v111, v100
	v_mov_b32_e32 v124, v100
	v_mov_b32_e32 v125, v96
	v_pk_mul_f32 v[110:111], v[110:111], v[120:121]
	v_pk_mul_f32 v[120:121], v[124:125], v[120:121]
	v_mov_b32_e32 v100, v97
	v_add_f32_e32 v96, v121, v120
	v_pk_mul_f32 v[120:121], v[100:101], v[122:123]
	v_sub_f32_e32 v110, v110, v111
	v_mul_f32_e32 v111, v117, v96
	v_sub_f32_e32 v96, v120, v121
	v_mul_f32_e32 v100, v117, v96
	v_mov_b32_e32 v96, v101
	v_mov_b32_e32 v120, v98
	v_mov_b32_e32 v121, v102
	v_pk_mul_f32 v[96:97], v[96:97], v[122:123]
	v_pk_mul_f32 v[120:121], v[120:121], v[112:113]
	v_add_f32_e32 v96, v97, v96
	v_sub_f32_e32 v97, v120, v121
	v_mov_b32_e32 v120, v102
	v_mov_b32_e32 v121, v98
	v_pk_mul_f32 v[112:113], v[120:121], v[112:113]
	v_mov_b32_e32 v102, v99
	v_add_f32_e32 v98, v113, v112
	v_pk_mul_f32 v[112:113], v[102:103], v[114:115]
	v_mul_f32_e32 v101, v117, v98
	v_sub_f32_e32 v98, v112, v113
	v_mul_f32_e32 v102, v117, v98
	v_mov_b32_e32 v98, v103
	v_pk_mul_f32 v[98:99], v[98:99], v[114:115]
	v_mul_f32_e32 v118, v117, v118
	v_add_f32_e32 v98, v99, v98
	v_mul_f32_e32 v104, v117, v104
	v_mul_f32_e32 v105, v117, v105
	v_mul_f32_e32 v108, v117, v108
	v_mul_f32_e32 v106, v117, v106
	v_mul_f32_e32 v107, v117, v107
	v_mul_f32_e32 v110, v117, v110
	v_mul_f32_e32 v96, v117, v96
	v_mul_f32_e32 v97, v117, v97
	v_mul_f32_e32 v98, v117, v98
	v_ashrrev_i32_e32 v117, 31, v116
	v_lshlrev_b64 v[112:113], s38, v[116:117]
	v_lshl_add_u64 v[112:113], v[112:113], 1, s[36:37]
	v_lshl_add_u64 v[112:113], v[112:113], 0, s[60:61]
	v_lshl_add_u64 v[116:117], v[162:163], 1, v[112:113]
	v_cvt_pk_bf16_f32 v112, v118, v104
	v_cvt_pk_bf16_f32 v113, v108, v106
	v_cvt_pk_bf16_f32 v114, v110, v100
	v_cvt_pk_bf16_f32 v115, v97, v102
	global_store_dwordx4 v[116:117], v[112:115], off
	s_nop 1
	v_cvt_pk_bf16_f32 v112, v119, v105
	v_cvt_pk_bf16_f32 v113, v109, v107
	v_cvt_pk_bf16_f32 v114, v111, v96
	v_cvt_pk_bf16_f32 v115, v101, v98
	global_store_dwordx4 v[116:117], v[112:115], off offset:256
	s_cbranch_vccnz .LBB0_559
	v_sub_u32_e32 v99, 0xef, v142
	v_cvt_f32_i32_e32 v99, v99
	s_add_u32 s2, s76, s86
	s_addc_u32 s3, s64, s87
	v_lshl_add_u64 v[112:113], s[2:3], 0, v[160:161]
	v_mul_f32_e32 v103, v170, v99
	v_cmp_gt_f32_e32 vcc, s75, v103
	v_lshl_add_u64 v[112:113], v[142:143], 1, v[112:113]
	s_nop 0
	v_cndmask_b32_e32 v103, 0, v190, vcc
	v_fmac_f32_e32 v103, v170, v99
	v_exp_f32_e32 v99, v103
	v_cndmask_b32_e32 v103, 0, v189, vcc
	v_ldexp_f32 v99, v99, v103
	v_mul_f32_e32 v103, v99, v118
	v_mul_f32_e32 v104, v99, v104
	v_cvt_pk_bf16_f32 v103, v103, v104
	v_mul_f32_e32 v104, v99, v119
	v_mul_f32_e32 v105, v99, v105
	v_cvt_pk_bf16_f32 v114, v104, v105
	v_add_co_u32_e32 v104, vcc, s33, v112
	ds_write_b16 v230, v103 offset:0
	ds_write_b16_d16_hi v230, v103 offset:32
	v_addc_co_u32_e32 v105, vcc, 0, v113, vcc
	v_mul_f32_e32 v103, v99, v108
	v_mul_f32_e32 v106, v99, v106
	ds_write_b16 v230, v114 offset:1024
	ds_write_b16_d16_hi v230, v114 offset:1056
	v_cvt_pk_bf16_f32 v103, v103, v106
	v_mul_f32_e32 v106, v99, v109
	v_mul_f32_e32 v107, v99, v107
	v_cvt_pk_bf16_f32 v106, v106, v107
	ds_write_b16 v230, v103 offset:64
	ds_write_b16_d16_hi v230, v103 offset:96
	ds_write_b16 v230, v106 offset:1088
	ds_write_b16_d16_hi v230, v106 offset:1120
	v_mul_f32_e32 v103, v99, v110
	v_mul_f32_e32 v100, v99, v100
	v_mul_f32_e32 v96, v99, v96
	v_cvt_pk_bf16_f32 v100, v103, v100
	v_mul_f32_e32 v103, v99, v111
	v_cvt_pk_bf16_f32 v96, v103, v96
	ds_write_b16 v230, v100 offset:128
	ds_write_b16_d16_hi v230, v100 offset:160
	ds_write_b16 v230, v96 offset:1152
	ds_write_b16_d16_hi v230, v96 offset:1184
	v_mul_f32_e32 v96, v99, v97
	v_mul_f32_e32 v97, v99, v102
	v_cvt_pk_bf16_f32 v96, v96, v97
	v_mul_f32_e32 v97, v99, v101
	v_mul_f32_e32 v98, v99, v98
	v_cvt_pk_bf16_f32 v97, v97, v98
	ds_write_b16 v230, v96 offset:192
	ds_write_b16_d16_hi v230, v96 offset:224
	ds_write_b16 v230, v97 offset:1216
	ds_write_b16_d16_hi v230, v97 offset:1248
	s_waitcnt lgkmcnt(0)
	ds_read_b128 v[234:237], v231
	ds_read_b128 v[238:241], v231 offset:1024
	v_lshl_add_u64 v[242:243], v[112:113], 0, v[232:233]
	s_waitcnt lgkmcnt(1)
	global_store_dwordx4 v[242:243], v[234:237], off offset:32
	v_lshl_add_u64 v[242:243], v[104:105], 0, v[232:233]
	s_waitcnt lgkmcnt(0)
	global_store_dwordx4 v[242:243], v[238:241], off offset:32
	s_waitcnt vmcnt(4)
	s_branch .Lrq_copy_2

; __device__ __forceinline__ unsigned cvt_pk_bf16(float lo, float hi) { unsigned r; asm volatile("v_cvt_pk_bf16_f32 %0, %1, %2" : "=v"(r) : "v"(lo), "v"(hi)); return r; }
;     __device__ __forceinline__ void operator()(const Acc& acc, const Unit& u, int wr, int wc, int fr, int fq) const {
;     ...
;             for (int m = 0; m < 4; ++m) {
;                 const int row_in = ai * HALF + wr * 64 + m * 16 + fr, s = u.pm * BM + row_in;
;                 const float rs = mode == 0 ? exp2f((float)(row_in + 1) * lg) : 0.0625f;
;                 const f32x4* cp = cs + ((size_t)s * 128 + wc * 32 + 8 * fq) / 2;
;                 f32x4 t[4];
; #pragma unroll
;                 for (int i = 0; i < 4; ++i) t[i] = cp[i];
;                 float o1[8], o2[8];
; #pragma unroll
;                 for (int n = 0; n < 2; ++n)
; #pragma unroll
;                     for (int j = 0; j < 4; ++j) { const int e = n * 4 + j; const float co = t[e >> 1][(e & 1) * 2], si = t[e >> 1][(e & 1) * 2 + 1];
;                         const float x1 = acc[ai][0][m][n][j], x2 = acc[ai][1][m][n][j];
;                         o1[e] = (x1 * co - x2 * si) * rs; o2[e] = (x2 * co + x1 * si) * rs; }
;                 bf16_t* rowp = O + u.coff + (size_t)row_in * ldc + wc * 32 + 8 * fq;
;                 u32x4 w; w.x = cvt_pk_bf16(o1[0], o1[1]); w.y = cvt_pk_bf16(o1[2], o1[3]); w.z = cvt_pk_bf16(o1[4], o1[5]); w.w = cvt_pk_bf16(o1[6], o1[7]);
;                 *(u32x4*)rowp = w;
;                 w.x = cvt_pk_bf16(o2[0], o2[1]); w.y = cvt_pk_bf16(o2[2], o2[3]); w.z = cvt_pk_bf16(o2[4], o2[5]); w.w = cvt_pk_bf16(o2[6], o2[7]);
;                 *(u32x4*)(rowp + HALF) = w;
;                 if (mode == 1) {
;                     const float z = exp2f((float)(255 - row_in) * lg);
;                     bf16_t* kz = KZ + u.coff + (size_t)(wc * 32 + 8 * fq) * 256 + row_in;
; #pragma unroll
;                     for (int e = 0; e < 8; e += 2) { const unsigned p1 = cvt_pk_bf16(o1[e] * z, o1[e + 1] * z), p2 = cvt_pk_bf16(o2[e] * z, o2[e + 1] * z);
;                         kz[(size_t)e * 256] = (bf16_t)(p1 & 0xffffu); kz[(size_t)(e + 1) * 256] = (bf16_t)(p1 >> 16);
;                         kz[(size_t)(e + HALF) * 256] = (bf16_t)(p2 & 0xffffu); kz[(size_t)(e + 1 + HALF) * 256] = (bf16_t)(p2 >> 16); }
;                 }
.Lrq_copy_2:
	v_add_u32_e32 v97, 33, v142
	v_cvt_f32_i32_e32 v97, v97
	v_add_u32_e32 v100, 32, v142
	v_add_u32_e32 v96, s20, v100
	v_mov_b32_e32 v116, v88
	v_mul_f32_e32 v98, v170, v97
	v_cmp_gt_f32_e32 vcc, s75, v98
	v_mov_b32_e32 v117, v92
	s_nop 0
	v_cndmask_b32_e32 v98, 0, v190, vcc
	v_fmac_f32_e32 v98, v170, v97
	v_exp_f32_e32 v97, v98
	v_cndmask_b32_e32 v98, 0, v189, vcc
	s_and_b64 vcc, exec, s[42:43]
	v_ldexp_f32 v101, v97, v98
	v_ashrrev_i32_e32 v97, 31, v96
	v_lshlrev_b64 v[96:97], 7, v[96:97]
	v_lshl_add_u64 v[96:97], v[96:97], 0, v[164:165]
	v_lshl_add_u64 v[102:103], v[96:97], 3, s[16:17]
	v_mov_b32_e32 v96, v196
	v_mov_b32_e32 v97, v197
	v_mov_b32_e32 v98, v198
	v_mov_b32_e32 v99, v199
	v_mov_b32_e32 v104, v200
	v_mov_b32_e32 v105, v201
	v_mov_b32_e32 v106, v202
	v_mov_b32_e32 v107, v203
	v_mov_b32_e32 v108, v204
	v_mov_b32_e32 v109, v205
	v_mov_b32_e32 v110, v206
	v_mov_b32_e32 v111, v207
	v_mov_b32_e32 v112, v208
	v_mov_b32_e32 v113, v209
	v_mov_b32_e32 v114, v210
	v_mov_b32_e32 v115, v211
	v_add_u32_e32 v228, 48, v142
	v_add_u32_e32 v228, s20, v228
	v_ashrrev_i32_e32 v229, 31, v228
	v_lshlrev_b64 v[228:229], 7, v[228:229]
	v_lshl_add_u64 v[228:229], v[228:229], 0, v[164:165]
	v_lshl_add_u64 v[228:229], v[228:229], 3, s[16:17]
	global_load_dwordx4 v[212:215], v[228:229], off offset:48
	global_load_dwordx4 v[216:219], v[228:229], off offset:32
	global_load_dwordx4 v[220:223], v[228:229], off offset:16
	global_load_dwordx4 v[224:227], v[228:229], off
	v_mov_b32_e32 v102, v92
	v_mov_b32_e32 v103, v88
	v_cndmask_b32_e64 v101, v191, v101, s[44:45]
	v_mov_b32_e32 v92, v89
	v_pk_mul_f32 v[102:103], v[102:103], v[112:113]
	v_pk_mul_f32 v[112:113], v[116:117], v[112:113]
	v_sub_f32_e32 v102, v102, v103
	v_add_f32_e32 v88, v113, v112
	v_mul_f32_e32 v103, v101, v88
	v_mov_b32_e32 v88, v93
	v_pk_mul_f32 v[112:113], v[88:89], v[114:115]
	v_pk_mul_f32 v[92:93], v[92:93], v[114:115]
	v_sub_f32_e32 v88, v112, v113
	v_add_f32_e32 v89, v93, v92
	v_mov_b32_e32 v92, v94
	v_mov_b32_e32 v93, v90
	v_mov_b32_e32 v112, v90
	v_mov_b32_e32 v113, v94
	v_pk_mul_f32 v[92:93], v[92:93], v[108:109]
	v_pk_mul_f32 v[108:109], v[112:113], v[108:109]
	v_sub_f32_e32 v92, v92, v93
	v_add_f32_e32 v90, v109, v108
	v_mul_f32_e32 v93, v101, v90
	v_mov_b32_e32 v90, v95
	v_mov_b32_e32 v94, v91
	v_pk_mul_f32 v[108:109], v[90:91], v[110:111]
	v_pk_mul_f32 v[94:95], v[94:95], v[110:111]
	v_sub_f32_e32 v90, v108, v109
	v_add_f32_e32 v91, v95, v94
	v_mov_b32_e32 v94, v80
	v_mov_b32_e32 v95, v84
	v_mov_b32_e32 v108, v84
	v_mov_b32_e32 v109, v80
	v_pk_mul_f32 v[94:95], v[94:95], v[104:105]
	v_pk_mul_f32 v[104:105], v[108:109], v[104:105]
	v_mov_b32_e32 v84, v81
	v_add_f32_e32 v80, v105, v104
	v_pk_mul_f32 v[104:105], v[84:85], v[106:107]
	v_sub_f32_e32 v94, v94, v95
	v_mul_f32_e32 v95, v101, v80
	v_sub_f32_e32 v80, v104, v105
	v_mul_f32_e32 v84, v101, v80
	v_mov_b32_e32 v80, v85
	v_mov_b32_e32 v104, v82
	v_mov_b32_e32 v105, v86
	v_pk_mul_f32 v[80:81], v[80:81], v[106:107]
	v_pk_mul_f32 v[104:105], v[104:105], v[96:97]
	v_add_f32_e32 v80, v81, v80
	v_sub_f32_e32 v81, v104, v105
	v_mov_b32_e32 v104, v86
	v_mov_b32_e32 v105, v82
	v_pk_mul_f32 v[96:97], v[104:105], v[96:97]
	v_mov_b32_e32 v86, v83
	v_add_f32_e32 v82, v97, v96
	v_pk_mul_f32 v[96:97], v[86:87], v[98:99]
	v_mul_f32_e32 v85, v101, v82
	v_sub_f32_e32 v82, v96, v97
	v_mul_f32_e32 v86, v101, v82
	v_mov_b32_e32 v82, v87
	v_pk_mul_f32 v[82:83], v[82:83], v[98:99]
	v_mul_f32_e32 v102, v101, v102
	v_add_f32_e32 v82, v83, v82
	v_mul_f32_e32 v88, v101, v88
	v_mul_f32_e32 v89, v101, v89
	v_mul_f32_e32 v92, v101, v92
	v_mul_f32_e32 v90, v101, v90
	v_mul_f32_e32 v91, v101, v91
	v_mul_f32_e32 v94, v101, v94
	v_mul_f32_e32 v80, v101, v80
	v_mul_f32_e32 v81, v101, v81
	v_mul_f32_e32 v82, v101, v82
	v_ashrrev_i32_e32 v101, 31, v100
	v_lshlrev_b64 v[96:97], s38, v[100:101]
	v_lshl_add_u64 v[96:97], v[96:97], 1, s[36:37]
	v_lshl_add_u64 v[96:97], v[96:97], 0, s[60:61]
	v_lshl_add_u64 v[100:101], v[162:163], 1, v[96:97]
	v_cvt_pk_bf16_f32 v96, v102, v88
	v_cvt_pk_bf16_f32 v97, v92, v90
	v_cvt_pk_bf16_f32 v98, v94, v84
	v_cvt_pk_bf16_f32 v99, v81, v86
	global_store_dwordx4 v[100:101], v[96:99], off
	s_nop 1
	v_cvt_pk_bf16_f32 v96, v103, v89
	v_cvt_pk_bf16_f32 v97, v93, v91
	v_cvt_pk_bf16_f32 v98, v95, v80
	v_cvt_pk_bf16_f32 v99, v85, v82
	global_store_dwordx4 v[100:101], v[96:99], off offset:256
	s_cbranch_vccnz .LBB0_561
	v_sub_u32_e32 v83, 0xdf, v142
	v_cvt_f32_i32_e32 v83, v83
	s_add_u32 s2, s76, s86
	s_addc_u32 s3, s64, s87
	v_lshl_add_u64 v[96:97], s[2:3], 0, v[160:161]
	v_mul_f32_e32 v87, v170, v83
	v_cmp_gt_f32_e32 vcc, s75, v87
	v_lshl_add_u64 v[96:97], v[142:143], 1, v[96:97]
	s_nop 0
	v_cndmask_b32_e32 v87, 0, v190, vcc
	v_fmac_f32_e32 v87, v170, v83
	v_exp_f32_e32 v83, v87
	v_cndmask_b32_e32 v87, 0, v189, vcc
	v_ldexp_f32 v83, v83, v87
	v_mul_f32_e32 v87, v83, v102
	v_mul_f32_e32 v88, v83, v88
	v_cvt_pk_bf16_f32 v87, v87, v88
	v_mul_f32_e32 v88, v83, v103
	v_mul_f32_e32 v89, v83, v89
	v_cvt_pk_bf16_f32 v98, v88, v89
	v_add_co_u32_e32 v88, vcc, s33, v96
	ds_write_b16 v230, v87 offset:0
	ds_write_b16_d16_hi v230, v87 offset:32
	v_addc_co_u32_e32 v89, vcc, 0, v97, vcc
	v_mul_f32_e32 v87, v83, v92
	v_mul_f32_e32 v90, v83, v90
	ds_write_b16 v230, v98 offset:1024
	ds_write_b16_d16_hi v230, v98 offset:1056
	v_cvt_pk_bf16_f32 v87, v87, v90
	v_mul_f32_e32 v90, v83, v93
	v_mul_f32_e32 v91, v83, v91
	v_cvt_pk_bf16_f32 v90, v90, v91
	ds_write_b16 v230, v87 offset:64
	ds_write_b16_d16_hi v230, v87 offset:96
	ds_write_b16 v230, v90 offset:1088
	ds_write_b16_d16_hi v230, v90 offset:1120
	v_mul_f32_e32 v87, v83, v94
	v_mul_f32_e32 v84, v83, v84
	v_mul_f32_e32 v80, v83, v80
	v_cvt_pk_bf16_f32 v84, v87, v84
	v_mul_f32_e32 v87, v83, v95
	v_cvt_pk_bf16_f32 v80, v87, v80
	ds_write_b16 v230, v84 offset:128
	ds_write_b16_d16_hi v230, v84 offset:160
	ds_write_b16 v230, v80 offset:1152
	ds_write_b16_d16_hi v230, v80 offset:1184
	v_mul_f32_e32 v80, v83, v81
	v_mul_f32_e32 v81, v83, v86
	v_cvt_pk_bf16_f32 v80, v80, v81
	v_mul_f32_e32 v81, v83, v85
	v_mul_f32_e32 v82, v83, v82
	v_cvt_pk_bf16_f32 v81, v81, v82
	ds_write_b16 v230, v80 offset:192
	ds_write_b16_d16_hi v230, v80 offset:224
	ds_write_b16 v230, v81 offset:1216
	ds_write_b16_d16_hi v230, v81 offset:1248
	s_waitcnt lgkmcnt(0)
	ds_read_b128 v[234:237], v231
	ds_read_b128 v[238:241], v231 offset:1024
	v_lshl_add_u64 v[242:243], v[96:97], 0, v[232:233]
	s_waitcnt lgkmcnt(1)
	global_store_dwordx4 v[242:243], v[234:237], off offset:64
	v_lshl_add_u64 v[242:243], v[88:89], 0, v[232:233]
	s_waitcnt lgkmcnt(0)
	global_store_dwordx4 v[242:243], v[238:241], off offset:64
	s_waitcnt vmcnt(4)
	s_branch .Lrq_copy_3

; __device__ __forceinline__ unsigned cvt_pk_bf16(float lo, float hi) { unsigned r; asm volatile("v_cvt_pk_bf16_f32 %0, %1, %2" : "=v"(r) : "v"(lo), "v"(hi)); return r; }
;     __device__ __forceinline__ void operator()(const Acc& acc, const Unit& u, int wr, int wc, int fr, int fq) const {
;     ...
;             for (int m = 0; m < 4; ++m) {
;                 const int row_in = ai * HALF + wr * 64 + m * 16 + fr, s = u.pm * BM + row_in;
;                 const float rs = mode == 0 ? exp2f((float)(row_in + 1) * lg) : 0.0625f;
;                 const f32x4* cp = cs + ((size_t)s * 128 + wc * 32 + 8 * fq) / 2;
;                 f32x4 t[4];
; #pragma unroll
;                 for (int i = 0; i < 4; ++i) t[i] = cp[i];
;                 float o1[8], o2[8];
; #pragma unroll
;                 for (int n = 0; n < 2; ++n)
; #pragma unroll
;                     for (int j = 0; j < 4; ++j) { const int e = n * 4 + j; const float co = t[e >> 1][(e & 1) * 2], si = t[e >> 1][(e & 1) * 2 + 1];
;                         const float x1 = acc[ai][0][m][n][j], x2 = acc[ai][1][m][n][j];
;                         o1[e] = (x1 * co - x2 * si) * rs; o2[e] = (x2 * co + x1 * si) * rs; }
;                 bf16_t* rowp = O + u.coff + (size_t)row_in * ldc + wc * 32 + 8 * fq;
;                 u32x4 w; w.x = cvt_pk_bf16(o1[0], o1[1]); w.y = cvt_pk_bf16(o1[2], o1[3]); w.z = cvt_pk_bf16(o1[4], o1[5]); w.w = cvt_pk_bf16(o1[6], o1[7]);
;                 *(u32x4*)rowp = w;
;                 w.x = cvt_pk_bf16(o2[0], o2[1]); w.y = cvt_pk_bf16(o2[2], o2[3]); w.z = cvt_pk_bf16(o2[4], o2[5]); w.w = cvt_pk_bf16(o2[6], o2[7]);
;                 *(u32x4*)(rowp + HALF) = w;
;                 if (mode == 1) {
;                     const float z = exp2f((float)(255 - row_in) * lg);
;                     bf16_t* kz = KZ + u.coff + (size_t)(wc * 32 + 8 * fq) * 256 + row_in;
; #pragma unroll
;                     for (int e = 0; e < 8; e += 2) { const unsigned p1 = cvt_pk_bf16(o1[e] * z, o1[e + 1] * z), p2 = cvt_pk_bf16(o2[e] * z, o2[e + 1] * z);
;                         kz[(size_t)e * 256] = (bf16_t)(p1 & 0xffffu); kz[(size_t)(e + 1) * 256] = (bf16_t)(p1 >> 16);
;                         kz[(size_t)(e + HALF) * 256] = (bf16_t)(p2 & 0xffffu); kz[(size_t)(e + 1 + HALF) * 256] = (bf16_t)(p2 >> 16); }
;                 }
.Lrq_copy_3:
	v_add_u32_e32 v81, 49, v142
	v_cvt_f32_i32_e32 v81, v81
	v_add_u32_e32 v84, 48, v142
	v_add_u32_e32 v80, s20, v84
	v_mov_b32_e32 v100, v72
	v_mul_f32_e32 v82, v170, v81
	v_cmp_gt_f32_e32 vcc, s75, v82
	v_mov_b32_e32 v101, v76
	s_nop 0
	v_cndmask_b32_e32 v82, 0, v190, vcc
	v_fmac_f32_e32 v82, v170, v81
	v_exp_f32_e32 v81, v82
	v_cndmask_b32_e32 v82, 0, v189, vcc
	s_and_b64 vcc, exec, s[42:43]
	v_ldexp_f32 v85, v81, v82
	v_ashrrev_i32_e32 v81, 31, v80
	v_lshlrev_b64 v[80:81], 7, v[80:81]
	v_lshl_add_u64 v[80:81], v[80:81], 0, v[164:165]
	v_lshl_add_u64 v[86:87], v[80:81], 3, s[16:17]
	v_mov_b32_e32 v80, v212
	v_mov_b32_e32 v81, v213
	v_mov_b32_e32 v82, v214
	v_mov_b32_e32 v83, v215
	v_mov_b32_e32 v88, v216
	v_mov_b32_e32 v89, v217
	v_mov_b32_e32 v90, v218
	v_mov_b32_e32 v91, v219
	v_mov_b32_e32 v92, v220
	v_mov_b32_e32 v93, v221
	v_mov_b32_e32 v94, v222
	v_mov_b32_e32 v95, v223
	v_mov_b32_e32 v96, v224
	v_mov_b32_e32 v97, v225
	v_mov_b32_e32 v98, v226
	v_mov_b32_e32 v99, v227
	v_add_u32_e32 v228, 0x80, v142
	v_add_u32_e32 v228, s20, v228
	v_ashrrev_i32_e32 v229, 31, v228
	v_lshlrev_b64 v[228:229], 7, v[228:229]
	v_lshl_add_u64 v[228:229], v[228:229], 0, v[164:165]
	v_lshl_add_u64 v[228:229], v[228:229], 3, s[16:17]
	global_load_dwordx4 v[196:199], v[228:229], off offset:48
	global_load_dwordx4 v[200:203], v[228:229], off offset:32
	global_load_dwordx4 v[204:207], v[228:229], off offset:16
	global_load_dwordx4 v[208:211], v[228:229], off
	v_mov_b32_e32 v86, v76
	v_mov_b32_e32 v87, v72
	v_cndmask_b32_e64 v85, v191, v85, s[44:45]
	v_mov_b32_e32 v76, v73
	v_pk_mul_f32 v[86:87], v[86:87], v[96:97]
	v_pk_mul_f32 v[96:97], v[100:101], v[96:97]
	v_sub_f32_e32 v86, v86, v87
	v_add_f32_e32 v72, v97, v96
	v_mul_f32_e32 v87, v85, v72
	v_mov_b32_e32 v72, v77
	v_pk_mul_f32 v[96:97], v[72:73], v[98:99]
	v_pk_mul_f32 v[76:77], v[76:77], v[98:99]
	v_sub_f32_e32 v72, v96, v97
	v_add_f32_e32 v73, v77, v76
	v_mov_b32_e32 v76, v78
	v_mov_b32_e32 v77, v74
	v_mov_b32_e32 v96, v74
	v_mov_b32_e32 v97, v78
	v_pk_mul_f32 v[76:77], v[76:77], v[92:93]
	v_pk_mul_f32 v[92:93], v[96:97], v[92:93]
	v_sub_f32_e32 v76, v76, v77
	v_add_f32_e32 v74, v93, v92
	v_mul_f32_e32 v77, v85, v74
	v_mov_b32_e32 v74, v79
	v_mov_b32_e32 v78, v75
	v_pk_mul_f32 v[92:93], v[74:75], v[94:95]
	v_pk_mul_f32 v[78:79], v[78:79], v[94:95]
	v_sub_f32_e32 v74, v92, v93
	v_add_f32_e32 v75, v79, v78
	v_mov_b32_e32 v78, v64
	v_mov_b32_e32 v79, v68
	v_mov_b32_e32 v92, v68
	v_mov_b32_e32 v93, v64
	v_pk_mul_f32 v[78:79], v[78:79], v[88:89]
	v_pk_mul_f32 v[88:89], v[92:93], v[88:89]
	v_mov_b32_e32 v68, v65
	v_add_f32_e32 v64, v89, v88
	v_pk_mul_f32 v[88:89], v[68:69], v[90:91]
	v_sub_f32_e32 v78, v78, v79
	v_mul_f32_e32 v79, v85, v64
	v_sub_f32_e32 v64, v88, v89
	v_mul_f32_e32 v68, v85, v64
	v_mov_b32_e32 v64, v69
	v_mov_b32_e32 v88, v66
	v_mov_b32_e32 v89, v70
	v_pk_mul_f32 v[64:65], v[64:65], v[90:91]
	v_pk_mul_f32 v[88:89], v[88:89], v[80:81]
	v_add_f32_e32 v64, v65, v64
	v_sub_f32_e32 v65, v88, v89
	v_mov_b32_e32 v88, v70
	v_mov_b32_e32 v89, v66
	v_pk_mul_f32 v[80:81], v[88:89], v[80:81]
	v_mov_b32_e32 v70, v67
	v_add_f32_e32 v66, v81, v80
	v_pk_mul_f32 v[80:81], v[70:71], v[82:83]
	v_mul_f32_e32 v69, v85, v66
	v_sub_f32_e32 v66, v80, v81
	v_mul_f32_e32 v70, v85, v66
	v_mov_b32_e32 v66, v71
	v_pk_mul_f32 v[66:67], v[66:67], v[82:83]
	v_mul_f32_e32 v86, v85, v86
	v_add_f32_e32 v66, v67, v66
	v_mul_f32_e32 v72, v85, v72
	v_mul_f32_e32 v73, v85, v73
	v_mul_f32_e32 v76, v85, v76
	v_mul_f32_e32 v74, v85, v74
	v_mul_f32_e32 v75, v85, v75
	v_mul_f32_e32 v78, v85, v78
	v_mul_f32_e32 v64, v85, v64
	v_mul_f32_e32 v65, v85, v65
	v_mul_f32_e32 v66, v85, v66
	v_ashrrev_i32_e32 v85, 31, v84
	v_lshlrev_b64 v[80:81], s38, v[84:85]
	v_lshl_add_u64 v[80:81], v[80:81], 1, s[36:37]
	v_lshl_add_u64 v[80:81], v[80:81], 0, s[60:61]
	v_lshl_add_u64 v[84:85], v[162:163], 1, v[80:81]
	v_cvt_pk_bf16_f32 v80, v86, v72
	v_cvt_pk_bf16_f32 v81, v76, v74
	v_cvt_pk_bf16_f32 v82, v78, v68
	v_cvt_pk_bf16_f32 v83, v65, v70
	global_store_dwordx4 v[84:85], v[80:83], off
	s_nop 1
	v_cvt_pk_bf16_f32 v80, v87, v73
	v_cvt_pk_bf16_f32 v81, v77, v75
	v_cvt_pk_bf16_f32 v82, v79, v64
	v_cvt_pk_bf16_f32 v83, v69, v66
	global_store_dwordx4 v[84:85], v[80:83], off offset:256
	s_cbranch_vccnz .LBB0_563
	v_sub_u32_e32 v67, 0xcf, v142
	v_cvt_f32_i32_e32 v67, v67
	s_add_u32 s2, s76, s86
	s_addc_u32 s3, s64, s87
	v_lshl_add_u64 v[80:81], s[2:3], 0, v[160:161]
	v_mul_f32_e32 v71, v170, v67
	v_cmp_gt_f32_e32 vcc, s75, v71
	v_lshl_add_u64 v[80:81], v[142:143], 1, v[80:81]
	s_nop 0
	v_cndmask_b32_e32 v71, 0, v190, vcc
	v_fmac_f32_e32 v71, v170, v67
	v_exp_f32_e32 v67, v71
	v_cndmask_b32_e32 v71, 0, v189, vcc
	v_ldexp_f32 v67, v67, v71
	v_mul_f32_e32 v71, v67, v86
	v_mul_f32_e32 v72, v67, v72
	v_cvt_pk_bf16_f32 v71, v71, v72
	v_mul_f32_e32 v72, v67, v87
	v_mul_f32_e32 v73, v67, v73
	v_cvt_pk_bf16_f32 v82, v72, v73
	v_add_co_u32_e32 v72, vcc, s33, v80
	ds_write_b16 v230, v71 offset:0
	ds_write_b16_d16_hi v230, v71 offset:32
	v_addc_co_u32_e32 v73, vcc, 0, v81, vcc
	v_mul_f32_e32 v71, v67, v76
	v_mul_f32_e32 v74, v67, v74
	ds_write_b16 v230, v82 offset:1024
	ds_write_b16_d16_hi v230, v82 offset:1056
	v_cvt_pk_bf16_f32 v71, v71, v74
	v_mul_f32_e32 v74, v67, v77
	v_mul_f32_e32 v75, v67, v75
	v_cvt_pk_bf16_f32 v74, v74, v75
	ds_write_b16 v230, v71 offset:64
	ds_write_b16_d16_hi v230, v71 offset:96
	ds_write_b16 v230, v74 offset:1088
	ds_write_b16_d16_hi v230, v74 offset:1120
	v_mul_f32_e32 v71, v67, v78
	v_mul_f32_e32 v68, v67, v68
	v_mul_f32_e32 v64, v67, v64
	v_cvt_pk_bf16_f32 v68, v71, v68
	v_mul_f32_e32 v71, v67, v79
	v_cvt_pk_bf16_f32 v64, v71, v64
	ds_write_b16 v230, v68 offset:128
	ds_write_b16_d16_hi v230, v68 offset:160
	ds_write_b16 v230, v64 offset:1152
	ds_write_b16_d16_hi v230, v64 offset:1184
	v_mul_f32_e32 v64, v67, v65
	v_mul_f32_e32 v65, v67, v70
	v_cvt_pk_bf16_f32 v64, v64, v65
	v_mul_f32_e32 v65, v67, v69
	v_mul_f32_e32 v66, v67, v66
	v_cvt_pk_bf16_f32 v65, v65, v66
	ds_write_b16 v230, v64 offset:192
	ds_write_b16_d16_hi v230, v64 offset:224
	ds_write_b16 v230, v65 offset:1216
	ds_write_b16_d16_hi v230, v65 offset:1248
	s_waitcnt lgkmcnt(0)
	ds_read_b128 v[234:237], v231
	ds_read_b128 v[238:241], v231 offset:1024
	v_lshl_add_u64 v[242:243], v[80:81], 0, v[232:233]
	s_waitcnt lgkmcnt(1)
	global_store_dwordx4 v[242:243], v[234:237], off offset:96
	v_lshl_add_u64 v[242:243], v[72:73], 0, v[232:233]
	s_waitcnt lgkmcnt(0)
	global_store_dwordx4 v[242:243], v[238:241], off offset:96
	s_waitcnt vmcnt(4)
	s_branch .Lrq_copy_4

; __device__ __forceinline__ unsigned cvt_pk_bf16(float lo, float hi) { unsigned r; asm volatile("v_cvt_pk_bf16_f32 %0, %1, %2" : "=v"(r) : "v"(lo), "v"(hi)); return r; }
;     __device__ __forceinline__ void operator()(const Acc& acc, const Unit& u, int wr, int wc, int fr, int fq) const {
;     ...
;             for (int m = 0; m < 4; ++m) {
;                 const int row_in = ai * HALF + wr * 64 + m * 16 + fr, s = u.pm * BM + row_in;
;                 const float rs = mode == 0 ? exp2f((float)(row_in + 1) * lg) : 0.0625f;
;                 const f32x4* cp = cs + ((size_t)s * 128 + wc * 32 + 8 * fq) / 2;
;                 f32x4 t[4];
; #pragma unroll
;                 for (int i = 0; i < 4; ++i) t[i] = cp[i];
;                 float o1[8], o2[8];
; #pragma unroll
;                 for (int n = 0; n < 2; ++n)
; #pragma unroll
;                     for (int j = 0; j < 4; ++j) { const int e = n * 4 + j; const float co = t[e >> 1][(e & 1) * 2], si = t[e >> 1][(e & 1) * 2 + 1];
;                         const float x1 = acc[ai][0][m][n][j], x2 = acc[ai][1][m][n][j];
;                         o1[e] = (x1 * co - x2 * si) * rs; o2[e] = (x2 * co + x1 * si) * rs; }
;                 bf16_t* rowp = O + u.coff + (size_t)row_in * ldc + wc * 32 + 8 * fq;
;                 u32x4 w; w.x = cvt_pk_bf16(o1[0], o1[1]); w.y = cvt_pk_bf16(o1[2], o1[3]); w.z = cvt_pk_bf16(o1[4], o1[5]); w.w = cvt_pk_bf16(o1[6], o1[7]);
;                 *(u32x4*)rowp = w;
;                 w.x = cvt_pk_bf16(o2[0], o2[1]); w.y = cvt_pk_bf16(o2[2], o2[3]); w.z = cvt_pk_bf16(o2[4], o2[5]); w.w = cvt_pk_bf16(o2[6], o2[7]);
;                 *(u32x4*)(rowp + HALF) = w;
;                 if (mode == 1) {
;                     const float z = exp2f((float)(255 - row_in) * lg);
;                     bf16_t* kz = KZ + u.coff + (size_t)(wc * 32 + 8 * fq) * 256 + row_in;
; #pragma unroll
;                     for (int e = 0; e < 8; e += 2) { const unsigned p1 = cvt_pk_bf16(o1[e] * z, o1[e + 1] * z), p2 = cvt_pk_bf16(o2[e] * z, o2[e + 1] * z);
;                         kz[(size_t)e * 256] = (bf16_t)(p1 & 0xffffu); kz[(size_t)(e + 1) * 256] = (bf16_t)(p1 >> 16);
;                         kz[(size_t)(e + HALF) * 256] = (bf16_t)(p2 & 0xffffu); kz[(size_t)(e + 1 + HALF) * 256] = (bf16_t)(p2 >> 16); }
;                 }
.Lrq_copy_4:
	v_add_u32_e32 v65, 0x81, v142
	v_cvt_f32_i32_e32 v65, v65
	v_add_u32_e32 v68, 0x80, v142
	v_add_u32_e32 v64, s20, v68
	v_mov_b32_e32 v84, v56
	v_mul_f32_e32 v66, v170, v65
	v_cmp_gt_f32_e32 vcc, s75, v66
	v_mov_b32_e32 v85, v60
	s_nop 0
	v_cndmask_b32_e32 v66, 0, v190, vcc
	v_fmac_f32_e32 v66, v170, v65
	v_exp_f32_e32 v65, v66
	v_cndmask_b32_e32 v66, 0, v189, vcc
	s_and_b64 vcc, exec, s[42:43]
	v_ldexp_f32 v69, v65, v66
	v_ashrrev_i32_e32 v65, 31, v64
	v_lshlrev_b64 v[64:65], 7, v[64:65]
	v_lshl_add_u64 v[64:65], v[64:65], 0, v[164:165]
	v_lshl_add_u64 v[70:71], v[64:65], 3, s[16:17]
	v_mov_b32_e32 v64, v196
	v_mov_b32_e32 v65, v197
	v_mov_b32_e32 v66, v198
	v_mov_b32_e32 v67, v199
	v_mov_b32_e32 v72, v200
	v_mov_b32_e32 v73, v201
	v_mov_b32_e32 v74, v202
	v_mov_b32_e32 v75, v203
	v_mov_b32_e32 v76, v204
	v_mov_b32_e32 v77, v205
	v_mov_b32_e32 v78, v206
	v_mov_b32_e32 v79, v207
	v_mov_b32_e32 v80, v208
	v_mov_b32_e32 v81, v209
	v_mov_b32_e32 v82, v210
	v_mov_b32_e32 v83, v211
	v_add_u32_e32 v228, 0x90, v142
	v_add_u32_e32 v228, s20, v228
	v_ashrrev_i32_e32 v229, 31, v228
	v_lshlrev_b64 v[228:229], 7, v[228:229]
	v_lshl_add_u64 v[228:229], v[228:229], 0, v[164:165]
	v_lshl_add_u64 v[228:229], v[228:229], 3, s[16:17]
	global_load_dwordx4 v[212:215], v[228:229], off offset:48
	global_load_dwordx4 v[216:219], v[228:229], off offset:32
	global_load_dwordx4 v[220:223], v[228:229], off offset:16
	global_load_dwordx4 v[224:227], v[228:229], off
	v_mov_b32_e32 v70, v60
	v_mov_b32_e32 v71, v56
	v_cndmask_b32_e64 v69, v191, v69, s[44:45]
	v_mov_b32_e32 v60, v57
	v_pk_mul_f32 v[70:71], v[70:71], v[80:81]
	v_pk_mul_f32 v[80:81], v[84:85], v[80:81]
	v_sub_f32_e32 v70, v70, v71
	v_add_f32_e32 v56, v81, v80
	v_mul_f32_e32 v71, v69, v56
	v_mov_b32_e32 v56, v61
	v_pk_mul_f32 v[80:81], v[56:57], v[82:83]
	v_pk_mul_f32 v[60:61], v[60:61], v[82:83]
	v_sub_f32_e32 v56, v80, v81
	v_add_f32_e32 v57, v61, v60
	v_mov_b32_e32 v60, v62
	v_mov_b32_e32 v61, v58
	v_mov_b32_e32 v80, v58
	v_mov_b32_e32 v81, v62
	v_pk_mul_f32 v[60:61], v[60:61], v[76:77]
	v_pk_mul_f32 v[76:77], v[80:81], v[76:77]
	v_sub_f32_e32 v60, v60, v61
	v_add_f32_e32 v58, v77, v76
	v_mul_f32_e32 v61, v69, v58
	v_mov_b32_e32 v58, v63
	v_mov_b32_e32 v62, v59
	v_pk_mul_f32 v[76:77], v[58:59], v[78:79]
	v_pk_mul_f32 v[62:63], v[62:63], v[78:79]
	v_sub_f32_e32 v58, v76, v77
	v_add_f32_e32 v59, v63, v62
	v_mov_b32_e32 v62, v48
	v_mov_b32_e32 v63, v52
	v_mov_b32_e32 v76, v52
	v_mov_b32_e32 v77, v48
	v_pk_mul_f32 v[62:63], v[62:63], v[72:73]
	v_pk_mul_f32 v[72:73], v[76:77], v[72:73]
	v_mov_b32_e32 v52, v49
	v_add_f32_e32 v48, v73, v72
	v_pk_mul_f32 v[72:73], v[52:53], v[74:75]
	v_sub_f32_e32 v62, v62, v63
	v_mul_f32_e32 v63, v69, v48
	v_sub_f32_e32 v48, v72, v73
	v_mul_f32_e32 v52, v69, v48
	v_mov_b32_e32 v48, v53
	v_mov_b32_e32 v72, v50
	v_mov_b32_e32 v73, v54
	v_pk_mul_f32 v[48:49], v[48:49], v[74:75]
	v_pk_mul_f32 v[72:73], v[72:73], v[64:65]
	v_add_f32_e32 v48, v49, v48
	v_sub_f32_e32 v49, v72, v73
	v_mov_b32_e32 v72, v54
	v_mov_b32_e32 v73, v50
	v_pk_mul_f32 v[64:65], v[72:73], v[64:65]
	v_mov_b32_e32 v54, v51
	v_add_f32_e32 v50, v65, v64
	v_pk_mul_f32 v[64:65], v[54:55], v[66:67]
	v_mul_f32_e32 v53, v69, v50
	v_sub_f32_e32 v50, v64, v65
	v_mul_f32_e32 v54, v69, v50
	v_mov_b32_e32 v50, v55
	v_pk_mul_f32 v[50:51], v[50:51], v[66:67]
	v_mul_f32_e32 v70, v69, v70
	v_add_f32_e32 v50, v51, v50
	v_mul_f32_e32 v56, v69, v56
	v_mul_f32_e32 v57, v69, v57
	v_mul_f32_e32 v60, v69, v60
	v_mul_f32_e32 v58, v69, v58
	v_mul_f32_e32 v59, v69, v59
	v_mul_f32_e32 v62, v69, v62
	v_mul_f32_e32 v48, v69, v48
	v_mul_f32_e32 v49, v69, v49
	v_mul_f32_e32 v50, v69, v50
	v_ashrrev_i32_e32 v69, 31, v68
	v_lshlrev_b64 v[64:65], s38, v[68:69]
	v_lshl_add_u64 v[64:65], v[64:65], 1, s[36:37]
	v_lshl_add_u64 v[64:65], v[64:65], 0, s[60:61]
	v_lshl_add_u64 v[68:69], v[162:163], 1, v[64:65]
	v_cvt_pk_bf16_f32 v64, v70, v56
	v_cvt_pk_bf16_f32 v65, v60, v58
	v_cvt_pk_bf16_f32 v66, v62, v52
	v_cvt_pk_bf16_f32 v67, v49, v54
	global_store_dwordx4 v[68:69], v[64:67], off
	s_nop 1
	v_cvt_pk_bf16_f32 v64, v71, v57
	v_cvt_pk_bf16_f32 v65, v61, v59
	v_cvt_pk_bf16_f32 v66, v63, v48
	v_cvt_pk_bf16_f32 v67, v53, v50
	global_store_dwordx4 v[68:69], v[64:67], off offset:256
	s_cbranch_vccnz .LBB0_565
	v_sub_u32_e32 v51, 0x7f, v142
	v_cvt_f32_i32_e32 v51, v51
	s_add_u32 s2, s76, s86
	s_addc_u32 s3, s64, s87
	v_lshl_add_u64 v[64:65], s[2:3], 0, v[160:161]
	v_mul_f32_e32 v55, v170, v51
	v_cmp_gt_f32_e32 vcc, s75, v55
	v_lshl_add_u64 v[64:65], v[142:143], 1, v[64:65]
	s_nop 0
	v_cndmask_b32_e32 v55, 0, v190, vcc
	v_fmac_f32_e32 v55, v170, v51
	v_exp_f32_e32 v51, v55
	v_cndmask_b32_e32 v55, 0, v189, vcc
	v_ldexp_f32 v51, v51, v55
	v_mul_f32_e32 v55, v51, v70
	v_mul_f32_e32 v56, v51, v56
	v_cvt_pk_bf16_f32 v55, v55, v56
	v_mul_f32_e32 v56, v51, v71
	v_mul_f32_e32 v57, v51, v57
	v_cvt_pk_bf16_f32 v66, v56, v57
	v_add_co_u32_e32 v56, vcc, s33, v64
	ds_write_b16 v230, v55 offset:0
	ds_write_b16_d16_hi v230, v55 offset:32
	v_addc_co_u32_e32 v57, vcc, 0, v65, vcc
	v_mul_f32_e32 v55, v51, v60
	v_mul_f32_e32 v58, v51, v58
	ds_write_b16 v230, v66 offset:1024
	ds_write_b16_d16_hi v230, v66 offset:1056
	v_cvt_pk_bf16_f32 v55, v55, v58
	v_mul_f32_e32 v58, v51, v61
	v_mul_f32_e32 v59, v51, v59
	v_cvt_pk_bf16_f32 v58, v58, v59
	ds_write_b16 v230, v55 offset:64
	ds_write_b16_d16_hi v230, v55 offset:96
	ds_write_b16 v230, v58 offset:1088
	ds_write_b16_d16_hi v230, v58 offset:1120
	v_mul_f32_e32 v55, v51, v62
	v_mul_f32_e32 v52, v51, v52
	v_mul_f32_e32 v48, v51, v48
	v_cvt_pk_bf16_f32 v52, v55, v52
	v_mul_f32_e32 v55, v51, v63
	v_cvt_pk_bf16_f32 v48, v55, v48
	ds_write_b16 v230, v52 offset:128
	ds_write_b16_d16_hi v230, v52 offset:160
	ds_write_b16 v230, v48 offset:1152
	ds_write_b16_d16_hi v230, v48 offset:1184
	v_mul_f32_e32 v48, v51, v49
	v_mul_f32_e32 v49, v51, v54
	v_cvt_pk_bf16_f32 v48, v48, v49
	v_mul_f32_e32 v49, v51, v53
	v_mul_f32_e32 v50, v51, v50
	v_cvt_pk_bf16_f32 v49, v49, v50
	ds_write_b16 v230, v48 offset:192
	ds_write_b16_d16_hi v230, v48 offset:224
	ds_write_b16 v230, v49 offset:1216
	ds_write_b16_d16_hi v230, v49 offset:1248
	s_waitcnt lgkmcnt(0)
	ds_read_b128 v[234:237], v231
	ds_read_b128 v[238:241], v231 offset:1024
	v_lshl_add_u64 v[242:243], v[64:65], 0, v[232:233]
	s_waitcnt lgkmcnt(1)
	global_store_dwordx4 v[242:243], v[234:237], off offset:256
	v_lshl_add_u64 v[242:243], v[56:57], 0, v[232:233]
	s_waitcnt lgkmcnt(0)
	global_store_dwordx4 v[242:243], v[238:241], off offset:256
	s_waitcnt vmcnt(4)
	s_branch .Lrq_copy_5

; __device__ __forceinline__ unsigned cvt_pk_bf16(float lo, float hi) { unsigned r; asm volatile("v_cvt_pk_bf16_f32 %0, %1, %2" : "=v"(r) : "v"(lo), "v"(hi)); return r; }
;     __device__ __forceinline__ void operator()(const Acc& acc, const Unit& u, int wr, int wc, int fr, int fq) const {
;     ...
;             for (int m = 0; m < 4; ++m) {
;                 const int row_in = ai * HALF + wr * 64 + m * 16 + fr, s = u.pm * BM + row_in;
;                 const float rs = mode == 0 ? exp2f((float)(row_in + 1) * lg) : 0.0625f;
;                 const f32x4* cp = cs + ((size_t)s * 128 + wc * 32 + 8 * fq) / 2;
;                 f32x4 t[4];
; #pragma unroll
;                 for (int i = 0; i < 4; ++i) t[i] = cp[i];
;                 float o1[8], o2[8];
; #pragma unroll
;                 for (int n = 0; n < 2; ++n)
; #pragma unroll
;                     for (int j = 0; j < 4; ++j) { const int e = n * 4 + j; const float co = t[e >> 1][(e & 1) * 2], si = t[e >> 1][(e & 1) * 2 + 1];
;                         const float x1 = acc[ai][0][m][n][j], x2 = acc[ai][1][m][n][j];
;                         o1[e] = (x1 * co - x2 * si) * rs; o2[e] = (x2 * co + x1 * si) * rs; }
;                 bf16_t* rowp = O + u.coff + (size_t)row_in * ldc + wc * 32 + 8 * fq;
;                 u32x4 w; w.x = cvt_pk_bf16(o1[0], o1[1]); w.y = cvt_pk_bf16(o1[2], o1[3]); w.z = cvt_pk_bf16(o1[4], o1[5]); w.w = cvt_pk_bf16(o1[6], o1[7]);
;                 *(u32x4*)rowp = w;
;                 w.x = cvt_pk_bf16(o2[0], o2[1]); w.y = cvt_pk_bf16(o2[2], o2[3]); w.z = cvt_pk_bf16(o2[4], o2[5]); w.w = cvt_pk_bf16(o2[6], o2[7]);
;                 *(u32x4*)(rowp + HALF) = w;
;                 if (mode == 1) {
;                     const float z = exp2f((float)(255 - row_in) * lg);
;                     bf16_t* kz = KZ + u.coff + (size_t)(wc * 32 + 8 * fq) * 256 + row_in;
; #pragma unroll
;                     for (int e = 0; e < 8; e += 2) { const unsigned p1 = cvt_pk_bf16(o1[e] * z, o1[e + 1] * z), p2 = cvt_pk_bf16(o2[e] * z, o2[e + 1] * z);
;                         kz[(size_t)e * 256] = (bf16_t)(p1 & 0xffffu); kz[(size_t)(e + 1) * 256] = (bf16_t)(p1 >> 16);
;                         kz[(size_t)(e + HALF) * 256] = (bf16_t)(p2 & 0xffffu); kz[(size_t)(e + 1 + HALF) * 256] = (bf16_t)(p2 >> 16); }
;                 }
.Lrq_copy_5:
	v_add_u32_e32 v49, 0x91, v142
	v_cvt_f32_i32_e32 v49, v49
	v_add_u32_e32 v52, 0x90, v142
	v_add_u32_e32 v48, s20, v52
	v_mov_b32_e32 v68, v40
	v_mul_f32_e32 v50, v170, v49
	v_cmp_gt_f32_e32 vcc, s75, v50
	v_mov_b32_e32 v69, v44
	s_nop 0
	v_cndmask_b32_e32 v50, 0, v190, vcc
	v_fmac_f32_e32 v50, v170, v49
	v_exp_f32_e32 v49, v50
	v_cndmask_b32_e32 v50, 0, v189, vcc
	s_and_b64 vcc, exec, s[42:43]
	v_ldexp_f32 v53, v49, v50
	v_ashrrev_i32_e32 v49, 31, v48
	v_lshlrev_b64 v[48:49], 7, v[48:49]
	v_lshl_add_u64 v[48:49], v[48:49], 0, v[164:165]
	v_lshl_add_u64 v[54:55], v[48:49], 3, s[16:17]
	v_mov_b32_e32 v48, v212
	v_mov_b32_e32 v49, v213
	v_mov_b32_e32 v50, v214
	v_mov_b32_e32 v51, v215
	v_mov_b32_e32 v56, v216
	v_mov_b32_e32 v57, v217
	v_mov_b32_e32 v58, v218
	v_mov_b32_e32 v59, v219
	v_mov_b32_e32 v60, v220
	v_mov_b32_e32 v61, v221
	v_mov_b32_e32 v62, v222
	v_mov_b32_e32 v63, v223
	v_mov_b32_e32 v64, v224
	v_mov_b32_e32 v65, v225
	v_mov_b32_e32 v66, v226
	v_mov_b32_e32 v67, v227
	v_add_u32_e32 v228, 0xa0, v142
	v_add_u32_e32 v228, s20, v228
	v_ashrrev_i32_e32 v229, 31, v228
	v_lshlrev_b64 v[228:229], 7, v[228:229]
	v_lshl_add_u64 v[228:229], v[228:229], 0, v[164:165]
	v_lshl_add_u64 v[228:229], v[228:229], 3, s[16:17]
	global_load_dwordx4 v[196:199], v[228:229], off offset:48
	global_load_dwordx4 v[200:203], v[228:229], off offset:32
	global_load_dwordx4 v[204:207], v[228:229], off offset:16
	global_load_dwordx4 v[208:211], v[228:229], off
	v_mov_b32_e32 v54, v44
	v_mov_b32_e32 v55, v40
	v_cndmask_b32_e64 v53, v191, v53, s[44:45]
	v_mov_b32_e32 v44, v41
	v_pk_mul_f32 v[54:55], v[54:55], v[64:65]
	v_pk_mul_f32 v[64:65], v[68:69], v[64:65]
	v_sub_f32_e32 v54, v54, v55
	v_add_f32_e32 v40, v65, v64
	v_mul_f32_e32 v55, v53, v40
	v_mov_b32_e32 v40, v45
	v_pk_mul_f32 v[64:65], v[40:41], v[66:67]
	v_pk_mul_f32 v[44:45], v[44:45], v[66:67]
	v_sub_f32_e32 v40, v64, v65
	v_add_f32_e32 v41, v45, v44
	v_mov_b32_e32 v44, v46
	v_mov_b32_e32 v45, v42
	v_mov_b32_e32 v64, v42
	v_mov_b32_e32 v65, v46
	v_pk_mul_f32 v[44:45], v[44:45], v[60:61]
	v_pk_mul_f32 v[60:61], v[64:65], v[60:61]
	v_sub_f32_e32 v44, v44, v45
	v_add_f32_e32 v42, v61, v60
	v_mul_f32_e32 v45, v53, v42
	v_mov_b32_e32 v42, v47
	v_mov_b32_e32 v46, v43
	v_pk_mul_f32 v[60:61], v[42:43], v[62:63]
	v_pk_mul_f32 v[46:47], v[46:47], v[62:63]
	v_sub_f32_e32 v42, v60, v61
	v_add_f32_e32 v43, v47, v46
	v_mov_b32_e32 v46, v32
	v_mov_b32_e32 v47, v36
	v_mov_b32_e32 v60, v36
	v_mov_b32_e32 v61, v32
	v_pk_mul_f32 v[46:47], v[46:47], v[56:57]
	v_pk_mul_f32 v[56:57], v[60:61], v[56:57]
	v_mov_b32_e32 v36, v33
	v_add_f32_e32 v32, v57, v56
	v_pk_mul_f32 v[56:57], v[36:37], v[58:59]
	v_sub_f32_e32 v46, v46, v47
	v_mul_f32_e32 v47, v53, v32
	v_sub_f32_e32 v32, v56, v57
	v_mul_f32_e32 v36, v53, v32
	v_mov_b32_e32 v32, v37
	v_mov_b32_e32 v56, v34
	v_mov_b32_e32 v57, v38
	v_pk_mul_f32 v[32:33], v[32:33], v[58:59]
	v_pk_mul_f32 v[56:57], v[56:57], v[48:49]
	v_add_f32_e32 v32, v33, v32
	v_sub_f32_e32 v33, v56, v57
	v_mov_b32_e32 v56, v38
	v_mov_b32_e32 v57, v34
	v_pk_mul_f32 v[48:49], v[56:57], v[48:49]
	v_mov_b32_e32 v38, v35
	v_add_f32_e32 v34, v49, v48
	v_pk_mul_f32 v[48:49], v[38:39], v[50:51]
	v_mul_f32_e32 v37, v53, v34
	v_sub_f32_e32 v34, v48, v49
	v_mul_f32_e32 v38, v53, v34
	v_mov_b32_e32 v34, v39
	v_pk_mul_f32 v[34:35], v[34:35], v[50:51]
	v_mul_f32_e32 v54, v53, v54
	v_add_f32_e32 v34, v35, v34
	v_mul_f32_e32 v40, v53, v40
	v_mul_f32_e32 v41, v53, v41
	v_mul_f32_e32 v44, v53, v44
	v_mul_f32_e32 v42, v53, v42
	v_mul_f32_e32 v43, v53, v43
	v_mul_f32_e32 v46, v53, v46
	v_mul_f32_e32 v32, v53, v32
	v_mul_f32_e32 v33, v53, v33
	v_mul_f32_e32 v34, v53, v34
	v_ashrrev_i32_e32 v53, 31, v52
	v_lshlrev_b64 v[48:49], s38, v[52:53]
	v_lshl_add_u64 v[48:49], v[48:49], 1, s[36:37]
	v_lshl_add_u64 v[48:49], v[48:49], 0, s[60:61]
	v_lshl_add_u64 v[52:53], v[162:163], 1, v[48:49]
	v_cvt_pk_bf16_f32 v48, v54, v40
	v_cvt_pk_bf16_f32 v49, v44, v42
	v_cvt_pk_bf16_f32 v50, v46, v36
	v_cvt_pk_bf16_f32 v51, v33, v38
	global_store_dwordx4 v[52:53], v[48:51], off
	s_nop 1
	v_cvt_pk_bf16_f32 v48, v55, v41
	v_cvt_pk_bf16_f32 v49, v45, v43
	v_cvt_pk_bf16_f32 v50, v47, v32
	v_cvt_pk_bf16_f32 v51, v37, v34
	global_store_dwordx4 v[52:53], v[48:51], off offset:256
	s_cbranch_vccnz .LBB0_567
	v_sub_u32_e32 v35, 0x6f, v142
	v_cvt_f32_i32_e32 v35, v35
	s_add_u32 s2, s76, s86
	s_addc_u32 s3, s64, s87
	v_lshl_add_u64 v[48:49], s[2:3], 0, v[160:161]
	v_mul_f32_e32 v39, v170, v35
	v_cmp_gt_f32_e32 vcc, s75, v39
	v_lshl_add_u64 v[48:49], v[142:143], 1, v[48:49]
	s_nop 0
	v_cndmask_b32_e32 v39, 0, v190, vcc
	v_fmac_f32_e32 v39, v170, v35
	v_exp_f32_e32 v35, v39
	v_cndmask_b32_e32 v39, 0, v189, vcc
	v_ldexp_f32 v35, v35, v39
	v_mul_f32_e32 v39, v35, v54
	v_mul_f32_e32 v40, v35, v40
	v_cvt_pk_bf16_f32 v39, v39, v40
	v_mul_f32_e32 v40, v35, v55
	v_mul_f32_e32 v41, v35, v41
	v_cvt_pk_bf16_f32 v50, v40, v41
	v_add_co_u32_e32 v40, vcc, s33, v48
	ds_write_b16 v230, v39 offset:0
	ds_write_b16_d16_hi v230, v39 offset:32
	v_addc_co_u32_e32 v41, vcc, 0, v49, vcc
	v_mul_f32_e32 v39, v35, v44
	v_mul_f32_e32 v42, v35, v42
	ds_write_b16 v230, v50 offset:1024
	ds_write_b16_d16_hi v230, v50 offset:1056
	v_cvt_pk_bf16_f32 v39, v39, v42
	v_mul_f32_e32 v42, v35, v45
	v_mul_f32_e32 v43, v35, v43
	v_cvt_pk_bf16_f32 v42, v42, v43
	ds_write_b16 v230, v39 offset:64
	ds_write_b16_d16_hi v230, v39 offset:96
	ds_write_b16 v230, v42 offset:1088
	ds_write_b16_d16_hi v230, v42 offset:1120
	v_mul_f32_e32 v39, v35, v46
	v_mul_f32_e32 v36, v35, v36
	v_mul_f32_e32 v32, v35, v32
	v_cvt_pk_bf16_f32 v36, v39, v36
	v_mul_f32_e32 v39, v35, v47
	v_cvt_pk_bf16_f32 v32, v39, v32
	ds_write_b16 v230, v36 offset:128
	ds_write_b16_d16_hi v230, v36 offset:160
	ds_write_b16 v230, v32 offset:1152
	ds_write_b16_d16_hi v230, v32 offset:1184
	v_mul_f32_e32 v32, v35, v33
	v_mul_f32_e32 v33, v35, v38
	v_cvt_pk_bf16_f32 v32, v32, v33
	v_mul_f32_e32 v33, v35, v37
	v_mul_f32_e32 v34, v35, v34
	v_cvt_pk_bf16_f32 v33, v33, v34
	ds_write_b16 v230, v32 offset:192
	ds_write_b16_d16_hi v230, v32 offset:224
	ds_write_b16 v230, v33 offset:1216
	ds_write_b16_d16_hi v230, v33 offset:1248
	s_waitcnt lgkmcnt(0)
	ds_read_b128 v[234:237], v231
	ds_read_b128 v[238:241], v231 offset:1024
	v_lshl_add_u64 v[242:243], v[48:49], 0, v[232:233]
	s_waitcnt lgkmcnt(1)
	global_store_dwordx4 v[242:243], v[234:237], off offset:288
	v_lshl_add_u64 v[242:243], v[40:41], 0, v[232:233]
	s_waitcnt lgkmcnt(0)
	global_store_dwordx4 v[242:243], v[238:241], off offset:288
	s_waitcnt vmcnt(4)
	s_branch .Lrq_copy_6

; __device__ __forceinline__ unsigned cvt_pk_bf16(float lo, float hi) { unsigned r; asm volatile("v_cvt_pk_bf16_f32 %0, %1, %2" : "=v"(r) : "v"(lo), "v"(hi)); return r; }
;     __device__ __forceinline__ void operator()(const Acc& acc, const Unit& u, int wr, int wc, int fr, int fq) const {
;     ...
;                 const int row_in = ai * HALF + wr * 64 + m * 16 + fr, s = u.pm * BM + row_in;
;                 const float rs = mode == 0 ? exp2f((float)(row_in + 1) * lg) : 0.0625f;
;                 const f32x4* cp = cs + ((size_t)s * 128 + wc * 32 + 8 * fq) / 2;
;                 f32x4 t[4];
; #pragma unroll
;                 for (int i = 0; i < 4; ++i) t[i] = cp[i];
;                 float o1[8], o2[8];
; #pragma unroll
;                 for (int n = 0; n < 2; ++n)
; #pragma unroll
;                     for (int j = 0; j < 4; ++j) { const int e = n * 4 + j; const float co = t[e >> 1][(e & 1) * 2], si = t[e >> 1][(e & 1) * 2 + 1];
;                         const float x1 = acc[ai][0][m][n][j], x2 = acc[ai][1][m][n][j];
;                         o1[e] = (x1 * co - x2 * si) * rs; o2[e] = (x2 * co + x1 * si) * rs; }
;                 bf16_t* rowp = O + u.coff + (size_t)row_in * ldc + wc * 32 + 8 * fq;
;                 u32x4 w; w.x = cvt_pk_bf16(o1[0], o1[1]); w.y = cvt_pk_bf16(o1[2], o1[3]); w.z = cvt_pk_bf16(o1[4], o1[5]); w.w = cvt_pk_bf16(o1[6], o1[7]);
;                 *(u32x4*)rowp = w;
;                 w.x = cvt_pk_bf16(o2[0], o2[1]); w.y = cvt_pk_bf16(o2[2], o2[3]); w.z = cvt_pk_bf16(o2[4], o2[5]); w.w = cvt_pk_bf16(o2[6], o2[7]);
;                 *(u32x4*)(rowp + HALF) = w;
;                 if (mode == 1) {
;                     const float z = exp2f((float)(255 - row_in) * lg);
;                     bf16_t* kz = KZ + u.coff + (size_t)(wc * 32 + 8 * fq) * 256 + row_in;
; #pragma unroll
;                     for (int e = 0; e < 8; e += 2) { const unsigned p1 = cvt_pk_bf16(o1[e] * z, o1[e + 1] * z), p2 = cvt_pk_bf16(o2[e] * z, o2[e + 1] * z);
;                         kz[(size_t)e * 256] = (bf16_t)(p1 & 0xffffu); kz[(size_t)(e + 1) * 256] = (bf16_t)(p1 >> 16);
;                         kz[(size_t)(e + HALF) * 256] = (bf16_t)(p2 & 0xffffu); kz[(size_t)(e + 1 + HALF) * 256] = (bf16_t)(p2 >> 16); }
.Lrq_copy_6:
	v_add_u32_e32 v33, 0xa1, v142
	v_cvt_f32_i32_e32 v33, v33
	v_add_u32_e32 v36, 0xa0, v142
	v_add_u32_e32 v32, s20, v36
	v_mov_b32_e32 v52, v24
	v_mul_f32_e32 v34, v170, v33
	v_cmp_gt_f32_e32 vcc, s75, v34
	v_mov_b32_e32 v53, v28
	s_nop 0
	v_cndmask_b32_e32 v34, 0, v190, vcc
	v_fmac_f32_e32 v34, v170, v33
	v_exp_f32_e32 v33, v34
	v_cndmask_b32_e32 v34, 0, v189, vcc
	s_and_b64 vcc, exec, s[42:43]
	v_ldexp_f32 v37, v33, v34
	v_ashrrev_i32_e32 v33, 31, v32
	v_lshlrev_b64 v[32:33], 7, v[32:33]
	v_lshl_add_u64 v[32:33], v[32:33], 0, v[164:165]
	v_lshl_add_u64 v[38:39], v[32:33], 3, s[16:17]
	v_mov_b32_e32 v32, v196
	v_mov_b32_e32 v33, v197
	v_mov_b32_e32 v34, v198
	v_mov_b32_e32 v35, v199
	v_mov_b32_e32 v40, v200
	v_mov_b32_e32 v41, v201
	v_mov_b32_e32 v42, v202
	v_mov_b32_e32 v43, v203
	v_mov_b32_e32 v44, v204
	v_mov_b32_e32 v45, v205
	v_mov_b32_e32 v46, v206
	v_mov_b32_e32 v47, v207
	v_mov_b32_e32 v48, v208
	v_mov_b32_e32 v49, v209
	v_mov_b32_e32 v50, v210
	v_mov_b32_e32 v51, v211
	v_add_u32_e32 v228, 0xb0, v142
	v_add_u32_e32 v228, s20, v228
	v_ashrrev_i32_e32 v229, 31, v228
	v_lshlrev_b64 v[228:229], 7, v[228:229]
	v_lshl_add_u64 v[228:229], v[228:229], 0, v[164:165]
	v_lshl_add_u64 v[228:229], v[228:229], 3, s[16:17]
	global_load_dwordx4 v[212:215], v[228:229], off offset:48
	global_load_dwordx4 v[216:219], v[228:229], off offset:32
	global_load_dwordx4 v[220:223], v[228:229], off offset:16
	global_load_dwordx4 v[224:227], v[228:229], off
	v_mov_b32_e32 v38, v28
	v_mov_b32_e32 v39, v24
	v_cndmask_b32_e64 v37, v191, v37, s[44:45]
	v_mov_b32_e32 v28, v25
	v_pk_mul_f32 v[38:39], v[38:39], v[48:49]
	v_pk_mul_f32 v[48:49], v[52:53], v[48:49]
	v_sub_f32_e32 v38, v38, v39
	v_add_f32_e32 v24, v49, v48
	v_mul_f32_e32 v39, v37, v24
	v_mov_b32_e32 v24, v29
	v_pk_mul_f32 v[48:49], v[24:25], v[50:51]
	v_pk_mul_f32 v[28:29], v[28:29], v[50:51]
	v_sub_f32_e32 v24, v48, v49
	v_add_f32_e32 v25, v29, v28
	v_mov_b32_e32 v28, v30
	v_mov_b32_e32 v29, v26
	v_mov_b32_e32 v48, v26
	v_mov_b32_e32 v49, v30
	v_pk_mul_f32 v[28:29], v[28:29], v[44:45]
	v_pk_mul_f32 v[44:45], v[48:49], v[44:45]
	v_sub_f32_e32 v28, v28, v29
	v_add_f32_e32 v26, v45, v44
	v_mul_f32_e32 v29, v37, v26
	v_mov_b32_e32 v26, v31
	v_mov_b32_e32 v30, v27
	v_pk_mul_f32 v[44:45], v[26:27], v[46:47]
	v_pk_mul_f32 v[30:31], v[30:31], v[46:47]
	v_sub_f32_e32 v26, v44, v45
	v_add_f32_e32 v27, v31, v30
	v_mov_b32_e32 v30, v16
	v_mov_b32_e32 v31, v20
	v_mov_b32_e32 v44, v20
	v_mov_b32_e32 v45, v16
	v_pk_mul_f32 v[30:31], v[30:31], v[40:41]
	v_pk_mul_f32 v[40:41], v[44:45], v[40:41]
	v_mov_b32_e32 v20, v17
	v_add_f32_e32 v16, v41, v40
	v_pk_mul_f32 v[40:41], v[20:21], v[42:43]
	v_sub_f32_e32 v30, v30, v31
	v_mul_f32_e32 v31, v37, v16
	v_sub_f32_e32 v16, v40, v41
	v_mul_f32_e32 v20, v37, v16
	v_mov_b32_e32 v16, v21
	v_mov_b32_e32 v40, v18
	v_mov_b32_e32 v41, v22
	v_pk_mul_f32 v[16:17], v[16:17], v[42:43]
	v_pk_mul_f32 v[40:41], v[40:41], v[32:33]
	v_add_f32_e32 v16, v17, v16
	v_sub_f32_e32 v17, v40, v41
	v_mov_b32_e32 v40, v22
	v_mov_b32_e32 v41, v18
	v_pk_mul_f32 v[32:33], v[40:41], v[32:33]
	v_mov_b32_e32 v22, v19
	v_add_f32_e32 v18, v33, v32
	v_pk_mul_f32 v[32:33], v[22:23], v[34:35]
	v_mul_f32_e32 v21, v37, v18
	v_sub_f32_e32 v18, v32, v33
	v_mul_f32_e32 v22, v37, v18
	v_mov_b32_e32 v18, v23
	v_pk_mul_f32 v[18:19], v[18:19], v[34:35]
	v_mul_f32_e32 v38, v37, v38
	v_add_f32_e32 v18, v19, v18
	v_mul_f32_e32 v24, v37, v24
	v_mul_f32_e32 v25, v37, v25
	v_mul_f32_e32 v28, v37, v28
	v_mul_f32_e32 v26, v37, v26
	v_mul_f32_e32 v27, v37, v27
	v_mul_f32_e32 v30, v37, v30
	v_mul_f32_e32 v16, v37, v16
	v_mul_f32_e32 v17, v37, v17
	v_mul_f32_e32 v18, v37, v18
	v_ashrrev_i32_e32 v37, 31, v36
	v_lshlrev_b64 v[32:33], s38, v[36:37]
	v_lshl_add_u64 v[32:33], v[32:33], 1, s[36:37]
	v_lshl_add_u64 v[32:33], v[32:33], 0, s[60:61]
	v_lshl_add_u64 v[36:37], v[162:163], 1, v[32:33]
	v_cvt_pk_bf16_f32 v32, v38, v24
	v_cvt_pk_bf16_f32 v33, v28, v26
	v_cvt_pk_bf16_f32 v34, v30, v20
	v_cvt_pk_bf16_f32 v35, v17, v22
	global_store_dwordx4 v[36:37], v[32:35], off
	s_nop 1
	v_cvt_pk_bf16_f32 v32, v39, v25
	v_cvt_pk_bf16_f32 v33, v29, v27
	v_cvt_pk_bf16_f32 v34, v31, v16
	v_cvt_pk_bf16_f32 v35, v21, v18
	global_store_dwordx4 v[36:37], v[32:35], off offset:256
	s_cbranch_vccnz .LBB0_569
	v_sub_u32_e32 v19, 0x5f, v142
	v_cvt_f32_i32_e32 v19, v19
	s_add_u32 s2, s76, s86
	s_addc_u32 s3, s64, s87
	v_lshl_add_u64 v[32:33], s[2:3], 0, v[160:161]
	v_mul_f32_e32 v23, v170, v19
	v_cmp_gt_f32_e32 vcc, s75, v23
	v_lshl_add_u64 v[32:33], v[142:143], 1, v[32:33]
	s_nop 0
	v_cndmask_b32_e32 v23, 0, v190, vcc
	v_fmac_f32_e32 v23, v170, v19
	v_exp_f32_e32 v19, v23
	v_cndmask_b32_e32 v23, 0, v189, vcc
	v_ldexp_f32 v19, v19, v23
	v_mul_f32_e32 v23, v19, v38
	v_mul_f32_e32 v24, v19, v24
	v_cvt_pk_bf16_f32 v23, v23, v24
	v_mul_f32_e32 v24, v19, v39
	v_mul_f32_e32 v25, v19, v25
	v_cvt_pk_bf16_f32 v34, v24, v25
	v_add_co_u32_e32 v24, vcc, s33, v32
	ds_write_b16 v230, v23 offset:0
	ds_write_b16_d16_hi v230, v23 offset:32
	v_addc_co_u32_e32 v25, vcc, 0, v33, vcc
	v_mul_f32_e32 v23, v19, v28
	v_mul_f32_e32 v26, v19, v26
	ds_write_b16 v230, v34 offset:1024
	ds_write_b16_d16_hi v230, v34 offset:1056
	v_cvt_pk_bf16_f32 v23, v23, v26
	v_mul_f32_e32 v26, v19, v29
	v_mul_f32_e32 v27, v19, v27
	v_cvt_pk_bf16_f32 v26, v26, v27
	ds_write_b16 v230, v23 offset:64
	ds_write_b16_d16_hi v230, v23 offset:96
	ds_write_b16 v230, v26 offset:1088
	ds_write_b16_d16_hi v230, v26 offset:1120
	v_mul_f32_e32 v23, v19, v30
	v_mul_f32_e32 v20, v19, v20
	v_mul_f32_e32 v16, v19, v16
	v_cvt_pk_bf16_f32 v20, v23, v20
	v_mul_f32_e32 v23, v19, v31
	v_cvt_pk_bf16_f32 v16, v23, v16
	ds_write_b16 v230, v20 offset:128
	ds_write_b16_d16_hi v230, v20 offset:160
	ds_write_b16 v230, v16 offset:1152
	ds_write_b16_d16_hi v230, v16 offset:1184
	v_mul_f32_e32 v16, v19, v17
	v_mul_f32_e32 v17, v19, v22
	v_cvt_pk_bf16_f32 v16, v16, v17
	v_mul_f32_e32 v17, v19, v21
	v_mul_f32_e32 v18, v19, v18
	v_cvt_pk_bf16_f32 v17, v17, v18
	ds_write_b16 v230, v16 offset:192
	ds_write_b16_d16_hi v230, v16 offset:224
	ds_write_b16 v230, v17 offset:1216
	ds_write_b16_d16_hi v230, v17 offset:1248
	s_waitcnt lgkmcnt(0)
	ds_read_b128 v[234:237], v231
	ds_read_b128 v[238:241], v231 offset:1024
	v_lshl_add_u64 v[242:243], v[32:33], 0, v[232:233]
	s_waitcnt lgkmcnt(1)
	global_store_dwordx4 v[242:243], v[234:237], off offset:320
	v_lshl_add_u64 v[242:243], v[24:25], 0, v[232:233]
	s_waitcnt lgkmcnt(0)
	global_store_dwordx4 v[242:243], v[238:241], off offset:320
	s_waitcnt vmcnt(4)
	s_branch .Lrq_copy_7

; __device__ __forceinline__ unsigned cvt_pk_bf16(float lo, float hi) { unsigned r; asm volatile("v_cvt_pk_bf16_f32 %0, %1, %2" : "=v"(r) : "v"(lo), "v"(hi)); return r; }
;     __device__ __forceinline__ void operator()(const Acc& acc, const Unit& u, int wr, int wc, int fr, int fq) const {
;     ...
;                 const int row_in = ai * HALF + wr * 64 + m * 16 + fr, s = u.pm * BM + row_in;
;                 const float rs = mode == 0 ? exp2f((float)(row_in + 1) * lg) : 0.0625f;
;                 const f32x4* cp = cs + ((size_t)s * 128 + wc * 32 + 8 * fq) / 2;
;                 f32x4 t[4];
; #pragma unroll
;                 for (int i = 0; i < 4; ++i) t[i] = cp[i];
;                 float o1[8], o2[8];
; #pragma unroll
;                 for (int n = 0; n < 2; ++n)
; #pragma unroll
;                     for (int j = 0; j < 4; ++j) { const int e = n * 4 + j; const float co = t[e >> 1][(e & 1) * 2], si = t[e >> 1][(e & 1) * 2 + 1];
;                         const float x1 = acc[ai][0][m][n][j], x2 = acc[ai][1][m][n][j];
;                         o1[e] = (x1 * co - x2 * si) * rs; o2[e] = (x2 * co + x1 * si) * rs; }
;                 bf16_t* rowp = O + u.coff + (size_t)row_in * ldc + wc * 32 + 8 * fq;
;                 u32x4 w; w.x = cvt_pk_bf16(o1[0], o1[1]); w.y = cvt_pk_bf16(o1[2], o1[3]); w.z = cvt_pk_bf16(o1[4], o1[5]); w.w = cvt_pk_bf16(o1[6], o1[7]);
;                 *(u32x4*)rowp = w;
;                 w.x = cvt_pk_bf16(o2[0], o2[1]); w.y = cvt_pk_bf16(o2[2], o2[3]); w.z = cvt_pk_bf16(o2[4], o2[5]); w.w = cvt_pk_bf16(o2[6], o2[7]);
;                 *(u32x4*)(rowp + HALF) = w;
;                 if (mode == 1) {
;                     const float z = exp2f((float)(255 - row_in) * lg);
;                     bf16_t* kz = KZ + u.coff + (size_t)(wc * 32 + 8 * fq) * 256 + row_in;
; #pragma unroll
;                     for (int e = 0; e < 8; e += 2) { const unsigned p1 = cvt_pk_bf16(o1[e] * z, o1[e + 1] * z), p2 = cvt_pk_bf16(o2[e] * z, o2[e + 1] * z);
;                         kz[(size_t)e * 256] = (bf16_t)(p1 & 0xffffu); kz[(size_t)(e + 1) * 256] = (bf16_t)(p1 >> 16);
;                         kz[(size_t)(e + HALF) * 256] = (bf16_t)(p2 & 0xffffu); kz[(size_t)(e + 1 + HALF) * 256] = (bf16_t)(p2 >> 16); }
.Lrq_copy_7:
	v_add_u32_e32 v17, 0xb1, v142
	v_cvt_f32_i32_e32 v17, v17
	v_add_u32_e32 v20, 0xb0, v142
	v_add_u32_e32 v16, s20, v20
	v_mov_b32_e32 v36, v8
	v_mul_f32_e32 v18, v170, v17
	v_cmp_gt_f32_e32 vcc, s75, v18
	v_mov_b32_e32 v37, v12
	s_nop 0
	v_cndmask_b32_e32 v18, 0, v190, vcc
	v_fmac_f32_e32 v18, v170, v17
	v_exp_f32_e32 v17, v18
	v_cndmask_b32_e32 v18, 0, v189, vcc
	s_and_b64 vcc, exec, s[42:43]
	v_ldexp_f32 v21, v17, v18
	v_ashrrev_i32_e32 v17, 31, v16
	v_lshlrev_b64 v[16:17], 7, v[16:17]
	v_lshl_add_u64 v[16:17], v[16:17], 0, v[164:165]
	v_lshl_add_u64 v[22:23], v[16:17], 3, s[16:17]
	v_mov_b32_e32 v16, v212
	v_mov_b32_e32 v17, v213
	v_mov_b32_e32 v18, v214
	v_mov_b32_e32 v19, v215
	v_mov_b32_e32 v24, v216
	v_mov_b32_e32 v25, v217
	v_mov_b32_e32 v26, v218
	v_mov_b32_e32 v27, v219
	v_mov_b32_e32 v28, v220
	v_mov_b32_e32 v29, v221
	v_mov_b32_e32 v30, v222
	v_mov_b32_e32 v31, v223
	v_mov_b32_e32 v32, v224
	v_mov_b32_e32 v33, v225
	v_mov_b32_e32 v34, v226
	v_mov_b32_e32 v35, v227
	v_mov_b32_e32 v22, v12
	v_mov_b32_e32 v23, v8
	v_cndmask_b32_e64 v21, v191, v21, s[44:45]
	v_mov_b32_e32 v12, v9
	v_pk_mul_f32 v[22:23], v[22:23], v[32:33]
	v_pk_mul_f32 v[32:33], v[36:37], v[32:33]
	v_sub_f32_e32 v22, v22, v23
	v_add_f32_e32 v8, v33, v32
	v_mul_f32_e32 v23, v21, v8
	v_mov_b32_e32 v8, v13
	v_pk_mul_f32 v[32:33], v[8:9], v[34:35]
	v_pk_mul_f32 v[12:13], v[12:13], v[34:35]
	v_sub_f32_e32 v8, v32, v33
	v_add_f32_e32 v9, v13, v12
	v_mov_b32_e32 v12, v14
	v_mov_b32_e32 v13, v10
	v_mov_b32_e32 v32, v10
	v_mov_b32_e32 v33, v14
	v_pk_mul_f32 v[12:13], v[12:13], v[28:29]
	v_pk_mul_f32 v[28:29], v[32:33], v[28:29]
	v_sub_f32_e32 v12, v12, v13
	v_add_f32_e32 v10, v29, v28
	v_mul_f32_e32 v13, v21, v10
	v_mov_b32_e32 v10, v15
	v_mov_b32_e32 v14, v11
	v_pk_mul_f32 v[28:29], v[10:11], v[30:31]
	v_pk_mul_f32 v[14:15], v[14:15], v[30:31]
	v_sub_f32_e32 v10, v28, v29
	v_add_f32_e32 v11, v15, v14
	v_mov_b32_e32 v14, v0
	v_mov_b32_e32 v15, v4
	v_mov_b32_e32 v28, v4
	v_mov_b32_e32 v29, v0
	v_pk_mul_f32 v[14:15], v[14:15], v[24:25]
	v_pk_mul_f32 v[24:25], v[28:29], v[24:25]
	v_mov_b32_e32 v4, v1
	v_add_f32_e32 v0, v25, v24
	v_pk_mul_f32 v[24:25], v[4:5], v[26:27]
	v_sub_f32_e32 v14, v14, v15
	v_mul_f32_e32 v15, v21, v0
	v_sub_f32_e32 v0, v24, v25
	v_mul_f32_e32 v4, v21, v0
	v_mov_b32_e32 v0, v5
	v_mov_b32_e32 v24, v2
	v_mov_b32_e32 v25, v6
	v_pk_mul_f32 v[0:1], v[0:1], v[26:27]
	v_pk_mul_f32 v[24:25], v[24:25], v[16:17]
	v_add_f32_e32 v0, v1, v0
	v_sub_f32_e32 v1, v24, v25
	v_mov_b32_e32 v24, v6
	v_mov_b32_e32 v25, v2
	v_pk_mul_f32 v[16:17], v[24:25], v[16:17]
	v_mov_b32_e32 v6, v3
	v_add_f32_e32 v2, v17, v16
	v_pk_mul_f32 v[16:17], v[6:7], v[18:19]
	v_mul_f32_e32 v5, v21, v2
	v_sub_f32_e32 v2, v16, v17
	v_mul_f32_e32 v6, v21, v2
	v_mov_b32_e32 v2, v7
	v_pk_mul_f32 v[2:3], v[2:3], v[18:19]
	v_mul_f32_e32 v22, v21, v22
	v_add_f32_e32 v2, v3, v2
	v_mul_f32_e32 v8, v21, v8
	v_mul_f32_e32 v9, v21, v9
	v_mul_f32_e32 v12, v21, v12
	v_mul_f32_e32 v10, v21, v10
	v_mul_f32_e32 v11, v21, v11
	v_mul_f32_e32 v14, v21, v14
	v_mul_f32_e32 v0, v21, v0
	v_mul_f32_e32 v1, v21, v1
	v_mul_f32_e32 v2, v21, v2
	v_ashrrev_i32_e32 v21, 31, v20
	v_lshlrev_b64 v[16:17], s38, v[20:21]
	v_lshl_add_u64 v[16:17], v[16:17], 1, s[36:37]
	v_lshl_add_u64 v[16:17], v[16:17], 0, s[60:61]
	v_lshl_add_u64 v[20:21], v[162:163], 1, v[16:17]
	v_cvt_pk_bf16_f32 v16, v22, v8
	v_cvt_pk_bf16_f32 v17, v12, v10
	v_cvt_pk_bf16_f32 v18, v14, v4
	v_cvt_pk_bf16_f32 v19, v1, v6
	global_store_dwordx4 v[20:21], v[16:19], off
	s_nop 1
	v_cvt_pk_bf16_f32 v16, v23, v9
	v_cvt_pk_bf16_f32 v17, v13, v11
	v_cvt_pk_bf16_f32 v18, v15, v0
	v_cvt_pk_bf16_f32 v19, v5, v2
	global_store_dwordx4 v[20:21], v[16:19], off offset:256
	s_cbranch_vccnz .LBB0_571
	v_sub_u32_e32 v3, 0x4f, v142
	v_cvt_f32_i32_e32 v3, v3
	s_add_u32 s2, s76, s86
	s_addc_u32 s3, s64, s87
	v_lshl_add_u64 v[16:17], s[2:3], 0, v[160:161]
	v_mul_f32_e32 v7, v170, v3
	v_cmp_gt_f32_e32 vcc, s75, v7
	v_lshl_add_u64 v[16:17], v[142:143], 1, v[16:17]
	s_nop 0
	v_cndmask_b32_e32 v7, 0, v190, vcc
	v_fmac_f32_e32 v7, v170, v3
	v_exp_f32_e32 v3, v7
	v_cndmask_b32_e32 v7, 0, v189, vcc
	v_ldexp_f32 v3, v3, v7
	v_mul_f32_e32 v7, v3, v22
	v_mul_f32_e32 v8, v3, v8
	v_cvt_pk_bf16_f32 v7, v7, v8
	v_mul_f32_e32 v8, v3, v23
	v_mul_f32_e32 v9, v3, v9
	v_cvt_pk_bf16_f32 v18, v8, v9
	v_add_co_u32_e32 v8, vcc, s33, v16
	ds_write_b16 v230, v7 offset:0
	ds_write_b16_d16_hi v230, v7 offset:32
	v_addc_co_u32_e32 v9, vcc, 0, v17, vcc
	v_mul_f32_e32 v7, v3, v12
	v_mul_f32_e32 v10, v3, v10
	ds_write_b16 v230, v18 offset:1024
	ds_write_b16_d16_hi v230, v18 offset:1056
	v_cvt_pk_bf16_f32 v7, v7, v10
	v_mul_f32_e32 v10, v3, v13
	v_mul_f32_e32 v11, v3, v11
	v_cvt_pk_bf16_f32 v10, v10, v11
	ds_write_b16 v230, v7 offset:64
	ds_write_b16_d16_hi v230, v7 offset:96
	ds_write_b16 v230, v10 offset:1088
	ds_write_b16_d16_hi v230, v10 offset:1120
	v_mul_f32_e32 v7, v3, v14
	v_mul_f32_e32 v4, v3, v4
	v_mul_f32_e32 v0, v3, v0
	v_cvt_pk_bf16_f32 v4, v7, v4
	v_mul_f32_e32 v7, v3, v15
	v_cvt_pk_bf16_f32 v0, v7, v0
	ds_write_b16 v230, v4 offset:128
	ds_write_b16_d16_hi v230, v4 offset:160
	ds_write_b16 v230, v0 offset:1152
	ds_write_b16_d16_hi v230, v0 offset:1184
	v_mul_f32_e32 v0, v3, v1
	v_mul_f32_e32 v1, v3, v6
	v_cvt_pk_bf16_f32 v0, v0, v1
	v_mul_f32_e32 v1, v3, v5
	v_mul_f32_e32 v2, v3, v2
	v_cvt_pk_bf16_f32 v1, v1, v2
	ds_write_b16 v230, v0 offset:192
	ds_write_b16_d16_hi v230, v0 offset:224
	ds_write_b16 v230, v1 offset:1216
	ds_write_b16_d16_hi v230, v1 offset:1248
	s_waitcnt lgkmcnt(0)
	ds_read_b128 v[234:237], v231
	ds_read_b128 v[238:241], v231 offset:1024
	v_lshl_add_u64 v[242:243], v[16:17], 0, v[232:233]
	s_waitcnt lgkmcnt(1)
	global_store_dwordx4 v[242:243], v[234:237], off offset:352
	v_lshl_add_u64 v[242:243], v[8:9], 0, v[232:233]
	s_waitcnt lgkmcnt(0)
	global_store_dwordx4 v[242:243], v[238:241], off offset:352

; __global__ void __launch_bounds__(NT, 2) fwd_megakernel(Args a) {
;     extern __shared__ __attribute__((aligned(16))) unsigned char lds_raw[];
	.amdhsa_kernel _Z14fwd_megakernel4Args
		.amdhsa_group_segment_fixed_size 16384
		.amdhsa_private_segment_fixed_size 0
		.amdhsa_kernarg_size 992
		.amdhsa_user_sgpr_count 2
		.amdhsa_user_sgpr_dispatch_ptr 0
		.amdhsa_user_sgpr_queue_ptr 0
		.amdhsa_user_sgpr_kernarg_segment_ptr 1
		.amdhsa_user_sgpr_dispatch_id 0
		.amdhsa_user_sgpr_kernarg_preload_length 0
		.amdhsa_user_sgpr_kernarg_preload_offset 0
		.amdhsa_user_sgpr_private_segment_size 0
		.amdhsa_uses_dynamic_stack 0
		.amdhsa_enable_private_segment 0
		.amdhsa_system_sgpr_workgroup_id_x 1
		.amdhsa_system_sgpr_workgroup_id_y 0
		.amdhsa_system_sgpr_workgroup_id_z 0
		.amdhsa_system_sgpr_workgroup_info 0
		.amdhsa_system_vgpr_workitem_id 2
		.amdhsa_next_free_vgpr 249
		.amdhsa_next_free_sgpr 100
		.amdhsa_accum_offset 252
		.amdhsa_reserve_vcc 1
		.amdhsa_float_round_mode_32 0
		.amdhsa_float_round_mode_16_64 0
		.amdhsa_float_denorm_mode_32 3
		.amdhsa_float_denorm_mode_16_64 3
		.amdhsa_dx10_clamp 1
		.amdhsa_ieee_mode 1
		.amdhsa_fp16_overflow 0
		.amdhsa_tg_split 0
		.amdhsa_exception_fp_ieee_invalid_op 0
		.amdhsa_exception_fp_denorm_src 0
		.amdhsa_exception_fp_ieee_div_zero 0
		.amdhsa_exception_fp_ieee_overflow 0
		.amdhsa_exception_fp_ieee_underflow 0
		.amdhsa_exception_fp_ieee_inexact 0
		.amdhsa_exception_int_div_zero 0
	.end_amdhsa_kernel

; __global__ void __launch_bounds__(NT, 2) fwd_megakernel(Args a) {
;     extern __shared__ __attribute__((aligned(16))) unsigned char lds_raw[];
amdhsa.kernels:
  - .agpr_count:     0
    .args:
      - .offset:         0
        .size:           736
        .value_kind:     by_value
      - .offset:         736
        .size:           4
        .value_kind:     hidden_block_count_x
      - .offset:         740
        .size:           4
        .value_kind:     hidden_block_count_y
      - .offset:         744
        .size:           4
        .value_kind:     hidden_block_count_z
      - .offset:         748
        .size:           2
        .value_kind:     hidden_group_size_x
      - .offset:         750
        .size:           2
        .value_kind:     hidden_group_size_y
      - .offset:         752
        .size:           2
        .value_kind:     hidden_group_size_z
      - .offset:         754
        .size:           2
        .value_kind:     hidden_remainder_x
      - .offset:         756
        .size:           2
        .value_kind:     hidden_remainder_y
      - .offset:         758
        .size:           2
        .value_kind:     hidden_remainder_z
      - .offset:         776
        .size:           8
        .value_kind:     hidden_global_offset_x
      - .offset:         784
        .size:           8
        .value_kind:     hidden_global_offset_y
      - .offset:         792
        .size:           8
        .value_kind:     hidden_global_offset_z
      - .offset:         800
        .size:           2
        .value_kind:     hidden_grid_dims
      - .offset:         824
        .size:           8
        .value_kind:     hidden_multigrid_sync_arg
      - .offset:         856
        .size:           4
        .value_kind:     hidden_dynamic_lds_size
    .group_segment_fixed_size: 16384
    .kernarg_segment_align: 8
    .kernarg_segment_size: 992
    .language:       OpenCL C
    .language_version:
      - 2
      - 0
    .max_flat_workgroup_size: 512
    .name:           _Z14fwd_megakernel4Args
    .private_segment_fixed_size: 0
    .sgpr_count:     106
    .sgpr_spill_count: 305
    .symbol:         _Z14fwd_megakernel4Args.kd
    .uniform_work_group_size: 1
    .uses_dynamic_stack: false
    .vgpr_count:     249
    .vgpr_spill_count: 0
    .wavefront_size: 64
